# deferred queue-ticket consumption in prologue, cache_tail and attention item loops (no vmcnt(0) right behind the atomic)
# baseline (speedup 1.0000x reference)
.LBB0_17:
	s_or_b64 exec, exec, s[44:45]
	s_waitcnt vmcnt(0)
	v_cmp_eq_u32_e64 s[4:5], 2, v24
	v_cvt_f32_f64_e32 v22, v[22:23]
	v_readfirstlane_b32 s10, v150
	v_cndmask_b32_e64 v26, v20, v18, s[4:5]
	v_cndmask_b32_e64 v27, -v21, -v19, s[4:5]
	v_cmp_eq_u32_e64 s[4:5], 1, v24
	s_nop 1
	v_cndmask_b32_e64 v20, v26, v20, s[4:5]
	v_cndmask_b32_e64 v21, v27, v21, s[4:5]
	v_cndmask_b32_e32 v19, v21, v19, vcc
	v_cndmask_b32_e32 v18, v20, v18, vcc
	v_cvt_f32_f64_e32 v23, v[18:19]
	v_lshl_or_b32 v18, v25, 6, v1
	v_ashrrev_i32_e32 v19, 31, v18
	v_lshlrev_b64 v[18:19], 2, v[18:19]
	v_lshl_add_u64 v[20:21], s[42:43], 0, v[18:19]
	v_lshl_add_u64 v[18:19], s[6:7], 0, v[18:19]
	v_add_co_u32_e32 v18, vcc, 0x1000000, v18
	global_store_dword v[20:21], v22, off
	s_nop 0
	v_addc_co_u32_e32 v19, vcc, 0, v19, vcc
	global_store_dword v[18:19], v23, off offset:128

.LBB0_19:
	v_mov_b32_e32 v88, v184
	v_mov_b32_e32 v97, 0
	v_cmp_eq_u32_e32 vcc, 0, v88
	s_and_saveexec_b64 s[4:5], vcc
	s_cbranch_execz .LBB0_23
	s_mov_b64 s[42:43], exec
	v_mbcnt_lo_u32_b32 v1, s42, 0
	v_mbcnt_hi_u32_b32 v1, s43, v1
	v_cmp_eq_u32_e32 vcc, 0, v1
	s_and_saveexec_b64 s[6:7], vcc
	s_cbranch_execz .LBB0_22
	s_bcnt1_i32_b64 s10, s[42:43]
	v_mov_b32_e32 v18, s10
	global_atomic_add v150, v63, v18, s[12:13] sc0
.LBB0_22:
	s_or_b64 exec, exec, s[6:7]
.LBB0_23:
	s_or_b64 exec, exec, s[4:5]
	s_cmpk_gt_i32 s40, 0xff
	s_mov_b64 s[4:5], -1
	s_cbranch_scc0 .LBB0_49
	s_cmpk_gt_u32 s40, 0x21ff
	s_cbranch_scc0 .LBB0_46
	s_cmpk_gt_u32 s40, 0x287f
	s_cbranch_scc0 .LBB0_41
	s_cmpk_gt_u32 s40, 0x2a7f
	s_cbranch_scc0 .LBB0_36
	s_load_dwordx2 s[4:5], s[8:9], 0xc0
	s_cmpk_gt_u32 s40, 0x2e7f
	s_mov_b64 s[6:7], -1
	s_cbranch_scc0 .LBB0_31
	s_load_dwordx2 s[42:43], s[8:9], 0xb0
	s_lshl_b32 s6, s40, 1
	s_lshl_b32 s10, s40, 5
	s_and_b32 s6, s6, 0x7fc0
	s_and_b32 s10, s10, 0x3e0
	s_add_i32 s6, s6, 0xa300
	s_lshl_b32 s44, s10, 2
	s_waitcnt lgkmcnt(0)
	s_add_u32 s42, s42, s44
	v_lshlrev_b32_e32 v1, 2, v88
	s_addc_u32 s43, s43, 0
	v_and_b32_e32 v62, 0x7c, v1
	v_ashrrev_i32_e32 v22, 5, v88
	v_lshl_add_u64 v[18:19], s[42:43], 0, v[62:63]
	s_and_b32 s42, s6, 0xffc0
	v_add_u32_e32 v26, 4, v22
	v_add_u32_e32 v30, 8, v22
	v_add_u32_e32 v34, 12, v22
	v_add_u32_e32 v38, 16, v22
	v_add_u32_e32 v42, 20, v22
	v_add_u32_e32 v46, 24, v22
	v_add_u32_e32 v50, 28, v22
	v_add_u32_e32 v24, s42, v22
	v_add_u32_e32 v28, s42, v26
	v_add_u32_e32 v32, s42, v30
	v_add_u32_e32 v36, s42, v34
	v_add_u32_e32 v40, s42, v38
	v_add_u32_e32 v44, s42, v42
	v_add_u32_e32 v48, s42, v46
	v_add_u32_e32 v52, s42, v50
	s_mov_b32 s7, 1
	v_add_u32_e32 v20, s62, v62
	v_mov_b32_e32 v1, v22
	v_mov_b32_e32 v21, v24
	v_mov_b32_e32 v23, v26
	v_mov_b32_e32 v25, v28
	v_mov_b32_e32 v27, v30
	v_mov_b32_e32 v29, v32
	v_mov_b32_e32 v31, v34
	v_mov_b32_e32 v33, v36
	v_mov_b32_e32 v35, v38
	v_mov_b32_e32 v37, v40
	v_mov_b32_e32 v39, v42
	v_mov_b32_e32 v41, v44
	v_mov_b32_e32 v43, v46
	v_mov_b32_e32 v45, v48
	v_mov_b32_e32 v47, v50
	v_mov_b32_e32 v49, v52
	s_mov_b32 s42, 0
	s_mov_b32 s43, 32
.LBB0_29:
	s_lshl_b32 s44, s42, 1
	s_lshl_b32 s45, s7, 1
	v_add_u32_e32 v56, s44, v24
	v_add_u32_e32 v54, s45, v21
	v_add_u32_e32 v58, s45, v25
	v_add_u32_e32 v60, s44, v28
	v_add_u32_e32 v90, s45, v29
	v_add_u32_e32 v92, s44, v32
	v_add_u32_e32 v98, s45, v33
	v_add_u32_e32 v100, s44, v36
	v_add_u32_e32 v102, s45, v37
	v_add_u32_e32 v104, s44, v40
	v_add_u32_e32 v106, s45, v41
	v_add_u32_e32 v108, s44, v44
	v_add_u32_e32 v110, s45, v45
	v_add_u32_e32 v112, s44, v48
	v_add_u32_e32 v114, s45, v49
	v_add_u32_e32 v116, s44, v52
	v_ashrrev_i32_e32 v57, 31, v56
	v_ashrrev_i32_e32 v55, 31, v54
	v_ashrrev_i32_e32 v61, 31, v60
	v_ashrrev_i32_e32 v59, 31, v58
	v_ashrrev_i32_e32 v93, 31, v92
	v_ashrrev_i32_e32 v91, 31, v90
	v_ashrrev_i32_e32 v101, 31, v100
	v_ashrrev_i32_e32 v99, 31, v98
	v_ashrrev_i32_e32 v105, 31, v104
	v_ashrrev_i32_e32 v103, 31, v102
	v_ashrrev_i32_e32 v109, 31, v108
	v_ashrrev_i32_e32 v107, 31, v106
	v_ashrrev_i32_e32 v113, 31, v112
	v_ashrrev_i32_e32 v111, 31, v110
	v_ashrrev_i32_e32 v117, 31, v116
	v_ashrrev_i32_e32 v115, 31, v114
	v_lshlrev_b64 v[56:57], 12, v[56:57]
	v_lshlrev_b64 v[54:55], 12, v[54:55]
	v_lshlrev_b64 v[58:59], 12, v[58:59]
	v_lshlrev_b64 v[60:61], 12, v[60:61]
	v_lshlrev_b64 v[90:91], 12, v[90:91]
	v_lshlrev_b64 v[92:93], 12, v[92:93]
	v_lshlrev_b64 v[98:99], 12, v[98:99]
	v_lshlrev_b64 v[100:101], 12, v[100:101]
	v_lshlrev_b64 v[102:103], 12, v[102:103]
	v_lshlrev_b64 v[104:105], 12, v[104:105]
	v_lshlrev_b64 v[106:107], 12, v[106:107]
	v_lshlrev_b64 v[108:109], 12, v[108:109]
	v_lshlrev_b64 v[110:111], 12, v[110:111]
	v_lshlrev_b64 v[112:113], 12, v[112:113]
	v_lshlrev_b64 v[114:115], 12, v[114:115]
	v_lshlrev_b64 v[116:117], 12, v[116:117]
	v_lshl_add_u64 v[56:57], v[18:19], 0, v[56:57]
	v_lshl_add_u64 v[54:55], v[18:19], 0, v[54:55]
	v_lshl_add_u64 v[60:61], v[18:19], 0, v[60:61]
	v_lshl_add_u64 v[58:59], v[18:19], 0, v[58:59]
	v_lshl_add_u64 v[92:93], v[18:19], 0, v[92:93]
	v_lshl_add_u64 v[90:91], v[18:19], 0, v[90:91]
	v_lshl_add_u64 v[100:101], v[18:19], 0, v[100:101]
	v_lshl_add_u64 v[98:99], v[18:19], 0, v[98:99]
	v_lshl_add_u64 v[104:105], v[18:19], 0, v[104:105]
	v_lshl_add_u64 v[102:103], v[18:19], 0, v[102:103]
	v_lshl_add_u64 v[108:109], v[18:19], 0, v[108:109]
	v_lshl_add_u64 v[106:107], v[18:19], 0, v[106:107]
	v_lshl_add_u64 v[112:113], v[18:19], 0, v[112:113]
	v_lshl_add_u64 v[110:111], v[18:19], 0, v[110:111]
	v_lshl_add_u64 v[116:117], v[18:19], 0, v[116:117]
	v_lshl_add_u64 v[114:115], v[18:19], 0, v[114:115]
	global_load_dword v51, v[56:57], off
	global_load_dword v53, v[54:55], off
	global_load_dword v62, v[60:61], off
	global_load_dword v82, v[58:59], off
	global_load_dword v86, v[92:93], off
	global_load_dword v89, v[90:91], off
	global_load_dword v118, v[100:101], off
	global_load_dword v119, v[98:99], off
	global_load_dword v120, v[104:105], off
	global_load_dword v121, v[102:103], off
	global_load_dword v122, v[108:109], off
	global_load_dword v123, v[106:107], off
	global_load_dword v124, v[112:113], off
	global_load_dword v125, v[110:111], off
	global_load_dword v126, v[116:117], off
	global_load_dword v127, v[114:115], off
	s_add_i32 s42, s42, 16
	s_add_i32 s7, s7, 16
	s_add_i32 s43, s43, -16
	v_add_u32_e32 v54, s44, v22
	v_add_u32_e32 v56, s45, v1
	v_add_u32_e32 v60, s45, v23
	v_add_u32_e32 v58, s44, v26
	v_add_u32_e32 v92, s45, v27
	v_add_u32_e32 v90, s44, v30
	v_add_u32_e32 v100, s45, v31
	v_add_u32_e32 v98, s44, v34
	v_add_u32_e32 v104, s45, v35
	v_add_u32_e32 v102, s44, v38
	v_add_u32_e32 v108, s45, v39
	v_add_u32_e32 v106, s44, v42
	v_add_u32_e32 v112, s45, v43
	v_add_u32_e32 v110, s44, v46
	v_add_u32_e32 v116, s45, v47
	v_add_u32_e32 v114, s44, v50
	s_cmp_lg_u32 s43, 0
	v_mad_u64_u32 v[54:55], s[44:45], v54, s63, v[20:21]
	v_mad_u64_u32 v[56:57], s[44:45], v56, s63, v[20:21]
	v_mad_u64_u32 v[58:59], s[44:45], v58, s63, v[20:21]
	v_mad_u64_u32 v[60:61], s[44:45], v60, s63, v[20:21]
	v_mad_u64_u32 v[90:91], s[44:45], v90, s63, v[20:21]
	v_mad_u64_u32 v[92:93], s[44:45], v92, s63, v[20:21]
	v_mad_u64_u32 v[98:99], s[44:45], v98, s63, v[20:21]
	v_mad_u64_u32 v[100:101], s[44:45], v100, s63, v[20:21]
	v_mad_u64_u32 v[102:103], s[44:45], v102, s63, v[20:21]
	v_mad_u64_u32 v[104:105], s[44:45], v104, s63, v[20:21]
	v_mad_u64_u32 v[106:107], s[44:45], v106, s63, v[20:21]
	v_mad_u64_u32 v[108:109], s[44:45], v108, s63, v[20:21]
	v_mad_u64_u32 v[110:111], s[44:45], v110, s63, v[20:21]
	v_mad_u64_u32 v[112:113], s[44:45], v112, s63, v[20:21]
	v_mad_u64_u32 v[114:115], s[44:45], v114, s63, v[20:21]
	v_mad_u64_u32 v[116:117], s[44:45], v116, s63, v[20:21]
	s_waitcnt vmcnt(15)
	ds_write_b32 v54, v51
	s_waitcnt vmcnt(14)
	ds_write_b32 v56, v53
	s_waitcnt vmcnt(13)
	ds_write_b32 v58, v62
	s_waitcnt vmcnt(12)
	ds_write_b32 v60, v82
	s_waitcnt vmcnt(11)
	ds_write_b32 v90, v86
	s_waitcnt vmcnt(10)
	ds_write_b32 v92, v89
	s_waitcnt vmcnt(9)
	ds_write_b32 v98, v118
	s_waitcnt vmcnt(8)
	ds_write_b32 v100, v119
	s_waitcnt vmcnt(7)
	ds_write_b32 v102, v120
	s_waitcnt vmcnt(6)
	ds_write_b32 v104, v121
	s_waitcnt vmcnt(5)
	ds_write_b32 v106, v122
	s_waitcnt vmcnt(4)
	ds_write_b32 v108, v123
	s_waitcnt vmcnt(3)
	ds_write_b32 v110, v124
	s_waitcnt vmcnt(2)
	ds_write_b32 v112, v125
	s_waitcnt vmcnt(1)
	ds_write_b32 v114, v126
	s_waitcnt vmcnt(0)
	ds_write_b32 v116, v127
	s_cbranch_scc1 .LBB0_29
	v_lshlrev_b32_e32 v18, 3, v88
	v_ashrrev_i32_e32 v1, 3, v88
	v_and_b32_e32 v20, 56, v18
	s_waitcnt lgkmcnt(0)
	v_mul_u32_u24_e32 v18, 0x84, v20
	v_lshlrev_b32_e32 v19, 2, v1
	v_add3_u32 v30, s62, v18, v19
	s_and_b32 s6, 0xffff, s6
	ds_read2_b32 v[18:19], v30 offset1:33
	s_and_b32 s10, 0xffff, s10
	s_lshl_b32 s6, s6, 1
	s_add_u32 s6, s4, s6
	s_addc_u32 s7, s5, 0
	v_lshlrev_b32_e32 v62, 1, v20
	v_lshl_add_u64 v[20:21], s[6:7], 0, v[62:63]
	v_lshl_add_u64 v[22:23], v[20:21], 0, s[16:17]
	s_waitcnt lgkmcnt(0)
	v_bfe_u32 v20, v18, 16, 1
	v_add3_u32 v18, v18, v20, s64
	ds_read2_b32 v[20:21], v30 offset0:66 offset1:99
	v_bfe_u32 v24, v19, 16, 1
	v_add3_u32 v19, v19, v24, s64
	ds_read2_b32 v[24:25], v30 offset0:132 offset1:165
	v_lshrrev_b32_e32 v18, 16, v18
	v_and_or_b32 v18, v19, s66, v18
	s_waitcnt lgkmcnt(1)
	v_bfe_u32 v19, v20, 16, 1
	v_add3_u32 v19, v20, v19, s64
	v_bfe_u32 v20, v21, 16, 1
	ds_read2_b32 v[26:27], v30 offset0:198 offset1:231
	v_lshrrev_b32_e32 v19, 16, v19
	v_add3_u32 v20, v21, v20, s64
	v_and_or_b32 v19, v20, s66, v19
	s_waitcnt lgkmcnt(1)
	v_bfe_u32 v20, v24, 16, 1
	v_add3_u32 v20, v24, v20, s64
	v_bfe_u32 v21, v25, 16, 1
	v_lshrrev_b32_e32 v20, 16, v20
	v_add3_u32 v21, v25, v21, s64
	v_and_or_b32 v20, v21, s66, v20
	s_waitcnt lgkmcnt(0)
	v_bfe_u32 v21, v26, 16, 1
	v_add3_u32 v21, v26, v21, s64
	v_bfe_u32 v24, v27, 16, 1
	v_lshrrev_b32_e32 v21, 16, v21
	v_add3_u32 v24, v27, v24, s64
	v_and_or_b32 v21, v24, s66, v21
	v_add_u32_e32 v24, s10, v1
	v_ashrrev_i32_e32 v25, 31, v24
	v_lshlrev_b64 v[26:27], 11, v[24:25]
	v_lshl_add_u64 v[26:27], v[22:23], 0, v[26:27]
	global_store_dwordx4 v[26:27], v[18:21], off sc0 sc1
	s_nop 1
	ds_read2_b32 v[18:19], v30 offset0:8 offset1:41
	ds_read2_b32 v[20:21], v30 offset0:74 offset1:107
	ds_read2_b32 v[26:27], v30 offset0:140 offset1:173
	ds_read2_b32 v[28:29], v30 offset0:206 offset1:239
	v_readfirstlane_b32 s10, v150
	s_waitcnt lgkmcnt(3)
	v_bfe_u32 v1, v18, 16, 1
	v_add3_u32 v1, v18, v1, s64
	v_bfe_u32 v18, v19, 16, 1
	v_lshrrev_b32_e32 v1, 16, v1
	v_add3_u32 v18, v19, v18, s64
	v_and_or_b32 v18, v18, s66, v1
	s_waitcnt lgkmcnt(2)
	v_bfe_u32 v1, v20, 16, 1
	v_add3_u32 v1, v20, v1, s64
	v_bfe_u32 v19, v21, 16, 1
	v_lshrrev_b32_e32 v1, 16, v1
	v_add3_u32 v19, v21, v19, s64
	v_and_or_b32 v19, v19, s66, v1
	s_waitcnt lgkmcnt(1)
	v_bfe_u32 v1, v26, 16, 1
	v_add3_u32 v1, v26, v1, s64
	v_bfe_u32 v20, v27, 16, 1
	v_lshrrev_b32_e32 v1, 16, v1
	v_add3_u32 v20, v27, v20, s64
	v_and_or_b32 v20, v20, s66, v1
	s_waitcnt lgkmcnt(0)
	v_bfe_u32 v1, v28, 16, 1
	v_add_u32_e32 v26, 8, v24
	v_add3_u32 v1, v28, v1, s64
	v_bfe_u32 v21, v29, 16, 1
	v_ashrrev_i32_e32 v27, 31, v26
	v_lshrrev_b32_e32 v1, 16, v1
	v_add3_u32 v21, v29, v21, s64
	v_lshlrev_b64 v[26:27], 11, v[26:27]
	v_and_or_b32 v21, v21, s66, v1
	v_lshl_add_u64 v[26:27], v[22:23], 0, v[26:27]
	global_store_dwordx4 v[26:27], v[18:21], off sc0 sc1
	s_nop 1
	ds_read2_b32 v[18:19], v30 offset0:16 offset1:49
	ds_read2_b32 v[20:21], v30 offset0:82 offset1:115
	ds_read2_b32 v[26:27], v30 offset0:148 offset1:181
	ds_read2_b32 v[28:29], v30 offset0:214 offset1:247
	s_mov_b64 s[6:7], 0
	s_waitcnt lgkmcnt(3)
	v_bfe_u32 v1, v18, 16, 1
	v_add3_u32 v1, v18, v1, s64
	v_bfe_u32 v18, v19, 16, 1
	v_lshrrev_b32_e32 v1, 16, v1
	v_add3_u32 v18, v19, v18, s64
	v_and_or_b32 v18, v18, s66, v1
	s_waitcnt lgkmcnt(2)
	v_bfe_u32 v1, v20, 16, 1
	v_add3_u32 v1, v20, v1, s64
	v_bfe_u32 v19, v21, 16, 1
	v_lshrrev_b32_e32 v1, 16, v1
	v_add3_u32 v19, v21, v19, s64
	v_and_or_b32 v19, v19, s66, v1
	s_waitcnt lgkmcnt(1)
	v_bfe_u32 v1, v26, 16, 1
	v_add3_u32 v1, v26, v1, s64
	v_bfe_u32 v20, v27, 16, 1
	v_lshrrev_b32_e32 v1, 16, v1
	v_add3_u32 v20, v27, v20, s64
	v_and_or_b32 v20, v20, s66, v1
	s_waitcnt lgkmcnt(0)
	v_bfe_u32 v1, v28, 16, 1
	v_add_u32_e32 v26, 16, v24
	v_add3_u32 v1, v28, v1, s64
	v_bfe_u32 v21, v29, 16, 1
	v_ashrrev_i32_e32 v27, 31, v26
	v_lshrrev_b32_e32 v1, 16, v1
	v_add3_u32 v21, v29, v21, s64
	v_lshlrev_b64 v[26:27], 11, v[26:27]
	v_and_or_b32 v21, v21, s66, v1
	v_lshl_add_u64 v[26:27], v[22:23], 0, v[26:27]
	global_store_dwordx4 v[26:27], v[18:21], off sc0 sc1
	s_nop 1
	ds_read2_b32 v[18:19], v30 offset0:24 offset1:57
	ds_read2_b32 v[20:21], v30 offset0:90 offset1:123
	ds_read2_b32 v[26:27], v30 offset0:156 offset1:189
	ds_read2_b32 v[28:29], v30 offset0:222 offset1:255
	v_add_u32_e32 v24, 24, v24
	s_waitcnt lgkmcnt(3)
	v_bfe_u32 v1, v18, 16, 1
	v_add3_u32 v1, v18, v1, s64
	v_bfe_u32 v18, v19, 16, 1
	v_lshrrev_b32_e32 v1, 16, v1
	v_add3_u32 v18, v19, v18, s64
	v_and_or_b32 v18, v18, s66, v1
	s_waitcnt lgkmcnt(2)
	v_bfe_u32 v1, v20, 16, 1
	v_add3_u32 v1, v20, v1, s64
	v_bfe_u32 v19, v21, 16, 1
	v_lshrrev_b32_e32 v1, 16, v1
	v_add3_u32 v19, v21, v19, s64
	v_and_or_b32 v19, v19, s66, v1
	s_waitcnt lgkmcnt(1)
	v_bfe_u32 v1, v26, 16, 1
	v_add3_u32 v1, v26, v1, s64
	v_bfe_u32 v20, v27, 16, 1
	v_lshrrev_b32_e32 v1, 16, v1
	v_add3_u32 v20, v27, v20, s64
	v_and_or_b32 v20, v20, s66, v1
	s_waitcnt lgkmcnt(0)
	v_bfe_u32 v1, v28, 16, 1
	v_add3_u32 v1, v28, v1, s64
	v_bfe_u32 v21, v29, 16, 1
	v_ashrrev_i32_e32 v25, 31, v24
	v_lshrrev_b32_e32 v1, 16, v1
	v_add3_u32 v21, v29, v21, s64
	v_lshlrev_b64 v[24:25], 11, v[24:25]
	v_and_or_b32 v21, v21, s66, v1
	v_lshl_add_u64 v[22:23], v[22:23], 0, v[24:25]
	global_store_dwordx4 v[22:23], v[18:21], off sc0 sc1
	s_nop 1
	s_waitcnt lgkmcnt(0)

.LBB0_33:
	s_lshl_b32 s44, s42, 1
	s_lshl_b32 s45, s10, 1
	v_add_u32_e32 v54, s45, v21
	v_add_u32_e32 v56, s44, v24
	v_add_u32_e32 v58, s45, v25
	v_add_u32_e32 v60, s44, v28
	v_add_u32_e32 v90, s45, v29
	v_add_u32_e32 v92, s44, v32
	v_add_u32_e32 v98, s45, v33
	v_add_u32_e32 v100, s44, v36
	v_add_u32_e32 v102, s45, v37
	v_add_u32_e32 v104, s44, v40
	v_add_u32_e32 v106, s45, v41
	v_add_u32_e32 v108, s44, v44
	v_add_u32_e32 v110, s45, v45
	v_add_u32_e32 v112, s44, v48
	v_add_u32_e32 v116, s44, v52
	v_add_u32_e32 v114, s45, v49
	v_ashrrev_i32_e32 v57, 31, v56
	v_ashrrev_i32_e32 v55, 31, v54
	v_ashrrev_i32_e32 v61, 31, v60
	v_ashrrev_i32_e32 v59, 31, v58
	v_ashrrev_i32_e32 v93, 31, v92
	v_ashrrev_i32_e32 v91, 31, v90
	v_ashrrev_i32_e32 v101, 31, v100
	v_ashrrev_i32_e32 v99, 31, v98
	v_ashrrev_i32_e32 v105, 31, v104
	v_ashrrev_i32_e32 v103, 31, v102
	v_ashrrev_i32_e32 v109, 31, v108
	v_ashrrev_i32_e32 v107, 31, v106
	v_ashrrev_i32_e32 v113, 31, v112
	v_ashrrev_i32_e32 v111, 31, v110
	v_ashrrev_i32_e32 v117, 31, v116
	v_ashrrev_i32_e32 v115, 31, v114
	v_lshlrev_b64 v[118:119], 13, v[54:55]
	v_lshlrev_b64 v[120:121], 13, v[56:57]
	v_lshl_add_u64 v[56:57], v[56:57], 2, s[14:15]
	v_lshl_add_u64 v[54:55], v[54:55], 2, s[14:15]
	v_lshlrev_b64 v[122:123], 13, v[58:59]
	v_lshlrev_b64 v[124:125], 13, v[60:61]
	v_lshl_add_u64 v[60:61], v[60:61], 2, s[14:15]
	v_lshl_add_u64 v[58:59], v[58:59], 2, s[14:15]
	v_lshlrev_b64 v[126:127], 13, v[90:91]
	v_lshlrev_b64 v[128:129], 13, v[92:93]
	v_lshl_add_u64 v[92:93], v[92:93], 2, s[14:15]
	v_lshl_add_u64 v[90:91], v[90:91], 2, s[14:15]
	v_lshlrev_b64 v[130:131], 13, v[98:99]
	v_lshlrev_b64 v[132:133], 13, v[100:101]
	v_lshl_add_u64 v[100:101], v[100:101], 2, s[14:15]
	v_lshl_add_u64 v[98:99], v[98:99], 2, s[14:15]
	v_lshlrev_b64 v[134:135], 13, v[102:103]
	v_lshlrev_b64 v[136:137], 13, v[104:105]
	v_lshl_add_u64 v[104:105], v[104:105], 2, s[14:15]
	v_lshl_add_u64 v[102:103], v[102:103], 2, s[14:15]
	v_lshlrev_b64 v[138:139], 13, v[106:107]
	v_lshlrev_b64 v[140:141], 13, v[108:109]
	v_lshl_add_u64 v[108:109], v[108:109], 2, s[14:15]
	v_lshl_add_u64 v[106:107], v[106:107], 2, s[14:15]
	v_lshlrev_b64 v[142:143], 13, v[110:111]
	v_lshlrev_b64 v[144:145], 13, v[112:113]
	v_lshl_add_u64 v[112:113], v[112:113], 2, s[14:15]
	v_lshl_add_u64 v[110:111], v[110:111], 2, s[14:15]
	v_lshlrev_b64 v[148:149], 13, v[116:117]
	v_lshlrev_b64 v[146:147], 13, v[114:115]
	v_lshl_add_u64 v[116:117], v[116:117], 2, s[14:15]
	v_lshl_add_u64 v[114:115], v[114:115], 2, s[14:15]
	global_load_dword v56, v[56:57], off
	s_nop 0
	global_load_dword v57, v[54:55], off
	v_lshl_add_u64 v[54:55], v[18:19], 0, v[124:125]
	global_load_dword v60, v[60:61], off
	s_nop 0
	global_load_dword v61, v[58:59], off
	v_lshl_add_u64 v[58:59], v[18:19], 0, v[128:129]
	global_load_dword v92, v[92:93], off
	s_nop 0
	global_load_dword v93, v[90:91], off
	v_lshl_add_u64 v[90:91], v[18:19], 0, v[132:133]
	global_load_dword v100, v[100:101], off
	s_nop 0
	global_load_dword v101, v[98:99], off
	v_lshl_add_u64 v[98:99], v[18:19], 0, v[136:137]
	global_load_dword v104, v[104:105], off
	s_nop 0
	global_load_dword v105, v[102:103], off
	v_lshl_add_u64 v[102:103], v[18:19], 0, v[140:141]
	global_load_dword v108, v[108:109], off
	s_nop 0
	global_load_dword v109, v[106:107], off
	v_lshl_add_u64 v[106:107], v[18:19], 0, v[144:145]
	global_load_dword v112, v[112:113], off
	s_nop 0
	global_load_dword v113, v[110:111], off
	v_lshl_add_u64 v[110:111], v[18:19], 0, v[148:149]
	v_lshl_add_u64 v[120:121], v[18:19], 0, v[120:121]
	v_lshl_add_u64 v[118:119], v[18:19], 0, v[118:119]
	v_lshl_add_u64 v[122:123], v[18:19], 0, v[122:123]
	v_lshl_add_u64 v[124:125], v[18:19], 0, v[126:127]
	v_lshl_add_u64 v[126:127], v[18:19], 0, v[130:131]
	v_lshl_add_u64 v[128:129], v[18:19], 0, v[134:135]
	v_lshl_add_u64 v[130:131], v[18:19], 0, v[138:139]
	v_lshl_add_u64 v[132:133], v[18:19], 0, v[142:143]
	v_lshl_add_u64 v[134:135], v[18:19], 0, v[146:147]
	global_load_dword v116, v[116:117], off
	s_nop 0
	global_load_dword v117, v[114:115], off
	s_nop 0
	global_load_dword v114, v[120:121], off
	global_load_dword v115, v[118:119], off
	s_nop 0
	global_load_dword v54, v[54:55], off
	s_nop 0
	global_load_dword v55, v[122:123], off
	s_nop 0
	global_load_dword v58, v[58:59], off
	s_nop 0
	global_load_dword v59, v[124:125], off
	s_nop 0
	global_load_dword v90, v[90:91], off
	s_nop 0
	global_load_dword v91, v[126:127], off
	s_nop 0
	global_load_dword v98, v[98:99], off
	s_nop 0
	global_load_dword v99, v[128:129], off
	s_nop 0
	global_load_dword v102, v[102:103], off
	s_nop 0
	global_load_dword v103, v[130:131], off
	s_nop 0
	global_load_dword v106, v[106:107], off
	s_nop 0
	global_load_dword v107, v[132:133], off
	s_nop 0
	global_load_dword v110, v[110:111], off
	s_nop 0
	global_load_dword v111, v[134:135], off
	s_add_i32 s42, s42, 16
	s_add_i32 s10, s10, 16
	s_add_i32 s43, s43, -16
	v_add_u32_e32 v53, s44, v22
	v_add_u32_e32 v51, s45, v1
	v_add_u32_e32 v62, s45, v23
	v_add_u32_e32 v82, s44, v26
	v_add_u32_e32 v86, s45, v27
	v_add_u32_e32 v89, s44, v30
	v_add_u32_e32 v132, s45, v31
	v_add_u32_e32 v130, s44, v34
	v_add_u32_e32 v136, s45, v35
	v_add_u32_e32 v134, s44, v38
	v_add_u32_e32 v140, s45, v39
	v_add_u32_e32 v138, s44, v42
	v_add_u32_e32 v144, s45, v43
	v_add_u32_e32 v142, s44, v46
	v_add_u32_e32 v148, s45, v47
	v_add_u32_e32 v146, s44, v50
	s_cmp_lg_u32 s43, 0
	v_mad_u64_u32 v[118:119], s[44:45], v53, s63, v[20:21]
	v_mad_u64_u32 v[120:121], s[44:45], v51, s63, v[20:21]
	v_mad_u64_u32 v[122:123], s[44:45], v82, s63, v[20:21]
	v_mad_u64_u32 v[124:125], s[44:45], v62, s63, v[20:21]
	v_mad_u64_u32 v[126:127], s[44:45], v89, s63, v[20:21]
	v_mad_u64_u32 v[128:129], s[44:45], v86, s63, v[20:21]
	v_mad_u64_u32 v[130:131], s[44:45], v130, s63, v[20:21]
	v_mad_u64_u32 v[132:133], s[44:45], v132, s63, v[20:21]
	v_mad_u64_u32 v[134:135], s[44:45], v134, s63, v[20:21]
	v_mad_u64_u32 v[136:137], s[44:45], v136, s63, v[20:21]
	v_mad_u64_u32 v[138:139], s[44:45], v138, s63, v[20:21]
	v_mad_u64_u32 v[140:141], s[44:45], v140, s63, v[20:21]
	v_mad_u64_u32 v[142:143], s[44:45], v142, s63, v[20:21]
	v_mad_u64_u32 v[144:145], s[44:45], v144, s63, v[20:21]
	v_mad_u64_u32 v[146:147], s[44:45], v146, s63, v[20:21]
	v_mad_u64_u32 v[148:149], s[44:45], v148, s63, v[20:21]
	s_waitcnt vmcnt(14)
	v_pk_mul_f32 v[56:57], v[114:115], v[56:57]
	s_waitcnt vmcnt(12)
	v_pk_mul_f32 v[54:55], v[54:55], v[60:61]
	s_waitcnt vmcnt(10)
	v_pk_mul_f32 v[58:59], v[58:59], v[92:93]
	s_waitcnt vmcnt(8)
	v_pk_mul_f32 v[60:61], v[90:91], v[100:101]
	s_waitcnt vmcnt(6)
	v_pk_mul_f32 v[90:91], v[98:99], v[104:105]
	s_waitcnt vmcnt(4)
	v_pk_mul_f32 v[92:93], v[102:103], v[108:109]
	s_waitcnt vmcnt(2)
	v_pk_mul_f32 v[98:99], v[106:107], v[112:113]
	s_waitcnt vmcnt(0)
	v_pk_mul_f32 v[100:101], v[110:111], v[116:117]
	ds_write_b32 v118, v56
	ds_write_b32 v120, v57
	ds_write_b32 v122, v54
	ds_write_b32 v124, v55
	ds_write_b32 v126, v58
	ds_write_b32 v128, v59
	ds_write_b32 v130, v60
	ds_write_b32 v132, v61
	ds_write_b32 v134, v90
	ds_write_b32 v136, v91
	ds_write_b32 v138, v92
	ds_write_b32 v140, v93
	ds_write_b32 v142, v98
	ds_write_b32 v144, v99
	ds_write_b32 v146, v100
	ds_write_b32 v148, v101
	s_cbranch_scc1 .LBB0_33
	v_lshlrev_b32_e32 v18, 3, v88
	v_ashrrev_i32_e32 v1, 3, v88
	v_and_b32_e32 v20, 56, v18
	s_waitcnt lgkmcnt(0)
	v_mul_u32_u24_e32 v18, 0x84, v20
	v_lshlrev_b32_e32 v19, 2, v1
	v_add3_u32 v30, s62, v18, v19
	s_and_b32 s6, 0xffff, s6
	ds_read2_b32 v[18:19], v30 offset1:33
	s_and_b32 s7, 0xffff, s7
	s_lshl_b32 s6, s6, 1
	s_add_u32 s4, s4, s6
	s_addc_u32 s5, s5, 0
	v_lshlrev_b32_e32 v62, 1, v20
	v_lshl_add_u64 v[20:21], s[4:5], 0, v[62:63]
	v_lshl_add_u64 v[22:23], v[20:21], 0, s[18:19]
	s_waitcnt lgkmcnt(0)
	v_bfe_u32 v20, v18, 16, 1
	v_add3_u32 v18, v18, v20, s64
	ds_read2_b32 v[20:21], v30 offset0:66 offset1:99
	v_bfe_u32 v24, v19, 16, 1
	v_add3_u32 v19, v19, v24, s64
	ds_read2_b32 v[24:25], v30 offset0:132 offset1:165
	v_lshrrev_b32_e32 v18, 16, v18
	v_and_or_b32 v18, v19, s66, v18
	s_waitcnt lgkmcnt(1)
	v_bfe_u32 v19, v20, 16, 1
	v_add3_u32 v19, v20, v19, s64
	v_bfe_u32 v20, v21, 16, 1
	ds_read2_b32 v[26:27], v30 offset0:198 offset1:231
	v_lshrrev_b32_e32 v19, 16, v19
	v_add3_u32 v20, v21, v20, s64
	v_and_or_b32 v19, v20, s66, v19
	s_waitcnt lgkmcnt(1)
	v_bfe_u32 v20, v24, 16, 1
	v_add3_u32 v20, v24, v20, s64
	v_bfe_u32 v21, v25, 16, 1
	v_lshrrev_b32_e32 v20, 16, v20
	v_add3_u32 v21, v25, v21, s64
	v_and_or_b32 v20, v21, s66, v20
	s_waitcnt lgkmcnt(0)
	v_bfe_u32 v21, v26, 16, 1
	v_add3_u32 v21, v26, v21, s64
	v_bfe_u32 v24, v27, 16, 1
	v_lshrrev_b32_e32 v21, 16, v21
	v_add3_u32 v24, v27, v24, s64
	v_and_or_b32 v21, v24, s66, v21
	v_add_u32_e32 v24, s7, v1
	v_ashrrev_i32_e32 v25, 31, v24
	v_lshlrev_b64 v[26:27], 11, v[24:25]
	v_lshl_add_u64 v[26:27], v[22:23], 0, v[26:27]
	global_store_dwordx4 v[26:27], v[18:21], off sc0 sc1
	s_nop 1
	ds_read2_b32 v[18:19], v30 offset0:8 offset1:41
	ds_read2_b32 v[20:21], v30 offset0:74 offset1:107
	ds_read2_b32 v[26:27], v30 offset0:140 offset1:173
	ds_read2_b32 v[28:29], v30 offset0:206 offset1:239
	v_readfirstlane_b32 s10, v150
	s_waitcnt lgkmcnt(3)
	v_bfe_u32 v1, v18, 16, 1
	v_add3_u32 v1, v18, v1, s64
	v_bfe_u32 v18, v19, 16, 1
	v_lshrrev_b32_e32 v1, 16, v1
	v_add3_u32 v18, v19, v18, s64
	v_and_or_b32 v18, v18, s66, v1
	s_waitcnt lgkmcnt(2)
	v_bfe_u32 v1, v20, 16, 1
	v_add3_u32 v1, v20, v1, s64
	v_bfe_u32 v19, v21, 16, 1
	v_lshrrev_b32_e32 v1, 16, v1
	v_add3_u32 v19, v21, v19, s64
	v_and_or_b32 v19, v19, s66, v1
	s_waitcnt lgkmcnt(1)
	v_bfe_u32 v1, v26, 16, 1
	v_add3_u32 v1, v26, v1, s64
	v_bfe_u32 v20, v27, 16, 1
	v_lshrrev_b32_e32 v1, 16, v1
	v_add3_u32 v20, v27, v20, s64
	v_and_or_b32 v20, v20, s66, v1
	s_waitcnt lgkmcnt(0)
	v_bfe_u32 v1, v28, 16, 1
	v_add_u32_e32 v26, 8, v24
	v_add3_u32 v1, v28, v1, s64
	v_bfe_u32 v21, v29, 16, 1
	v_ashrrev_i32_e32 v27, 31, v26
	v_lshrrev_b32_e32 v1, 16, v1
	v_add3_u32 v21, v29, v21, s64
	v_lshlrev_b64 v[26:27], 11, v[26:27]
	v_and_or_b32 v21, v21, s66, v1
	v_lshl_add_u64 v[26:27], v[22:23], 0, v[26:27]
	global_store_dwordx4 v[26:27], v[18:21], off sc0 sc1
	s_nop 1
	ds_read2_b32 v[18:19], v30 offset0:16 offset1:49
	ds_read2_b32 v[20:21], v30 offset0:82 offset1:115
	ds_read2_b32 v[26:27], v30 offset0:148 offset1:181
	ds_read2_b32 v[28:29], v30 offset0:214 offset1:247
	s_waitcnt lgkmcnt(3)
	v_bfe_u32 v1, v18, 16, 1
	v_add3_u32 v1, v18, v1, s64
	v_bfe_u32 v18, v19, 16, 1
	v_lshrrev_b32_e32 v1, 16, v1
	v_add3_u32 v18, v19, v18, s64
	v_and_or_b32 v18, v18, s66, v1
	s_waitcnt lgkmcnt(2)
	v_bfe_u32 v1, v20, 16, 1
	v_add3_u32 v1, v20, v1, s64
	v_bfe_u32 v19, v21, 16, 1
	v_lshrrev_b32_e32 v1, 16, v1
	v_add3_u32 v19, v21, v19, s64
	v_and_or_b32 v19, v19, s66, v1
	s_waitcnt lgkmcnt(1)
	v_bfe_u32 v1, v26, 16, 1
	v_add3_u32 v1, v26, v1, s64
	v_bfe_u32 v20, v27, 16, 1
	v_lshrrev_b32_e32 v1, 16, v1
	v_add3_u32 v20, v27, v20, s64
	v_and_or_b32 v20, v20, s66, v1
	s_waitcnt lgkmcnt(0)
	v_bfe_u32 v1, v28, 16, 1
	v_add_u32_e32 v26, 16, v24
	v_add3_u32 v1, v28, v1, s64
	v_bfe_u32 v21, v29, 16, 1
	v_ashrrev_i32_e32 v27, 31, v26
	v_lshrrev_b32_e32 v1, 16, v1
	v_add3_u32 v21, v29, v21, s64
	v_lshlrev_b64 v[26:27], 11, v[26:27]
	v_and_or_b32 v21, v21, s66, v1
	v_lshl_add_u64 v[26:27], v[22:23], 0, v[26:27]
	global_store_dwordx4 v[26:27], v[18:21], off sc0 sc1
	s_nop 1
	ds_read2_b32 v[18:19], v30 offset0:24 offset1:57
	ds_read2_b32 v[20:21], v30 offset0:90 offset1:123
	ds_read2_b32 v[26:27], v30 offset0:156 offset1:189
	ds_read2_b32 v[28:29], v30 offset0:222 offset1:255
	v_add_u32_e32 v24, 24, v24
	s_waitcnt lgkmcnt(3)
	v_bfe_u32 v1, v18, 16, 1
	v_add3_u32 v1, v18, v1, s64
	v_bfe_u32 v18, v19, 16, 1
	v_lshrrev_b32_e32 v1, 16, v1
	v_add3_u32 v18, v19, v18, s64
	v_and_or_b32 v18, v18, s66, v1
	s_waitcnt lgkmcnt(2)
	v_bfe_u32 v1, v20, 16, 1
	v_add3_u32 v1, v20, v1, s64
	v_bfe_u32 v19, v21, 16, 1
	v_lshrrev_b32_e32 v1, 16, v1
	v_add3_u32 v19, v21, v19, s64
	v_and_or_b32 v19, v19, s66, v1
	s_waitcnt lgkmcnt(1)
	v_bfe_u32 v1, v26, 16, 1
	v_add3_u32 v1, v26, v1, s64
	v_bfe_u32 v20, v27, 16, 1
	v_lshrrev_b32_e32 v1, 16, v1
	v_add3_u32 v20, v27, v20, s64
	v_and_or_b32 v20, v20, s66, v1
	s_waitcnt lgkmcnt(0)
	v_bfe_u32 v1, v28, 16, 1
	v_add3_u32 v1, v28, v1, s64
	v_bfe_u32 v21, v29, 16, 1
	v_ashrrev_i32_e32 v25, 31, v24
	v_lshrrev_b32_e32 v1, 16, v1
	v_add3_u32 v21, v29, v21, s64
	v_lshlrev_b64 v[24:25], 11, v[24:25]
	v_and_or_b32 v21, v21, s66, v1
	v_lshl_add_u64 v[22:23], v[22:23], 0, v[24:25]
	global_store_dwordx4 v[22:23], v[18:21], off sc0 sc1
	s_nop 1
	s_waitcnt lgkmcnt(0)

.LBB0_38:
	s_lshl_b32 s44, s42, 1
	s_lshl_b32 s45, s7, 1
	v_add_u32_e32 v56, s44, v24
	v_add_u32_e32 v54, s45, v21
	v_add_u32_e32 v58, s45, v25
	v_add_u32_e32 v60, s44, v28
	v_add_u32_e32 v90, s45, v29
	v_add_u32_e32 v92, s44, v32
	v_add_u32_e32 v98, s45, v33
	v_add_u32_e32 v100, s44, v36
	v_add_u32_e32 v102, s45, v37
	v_add_u32_e32 v104, s44, v40
	v_add_u32_e32 v106, s45, v41
	v_add_u32_e32 v108, s44, v44
	v_add_u32_e32 v110, s45, v45
	v_add_u32_e32 v112, s44, v48
	v_add_u32_e32 v114, s45, v49
	v_add_u32_e32 v116, s44, v52
	v_ashrrev_i32_e32 v57, 31, v56
	v_ashrrev_i32_e32 v55, 31, v54
	v_ashrrev_i32_e32 v61, 31, v60
	v_ashrrev_i32_e32 v59, 31, v58
	v_ashrrev_i32_e32 v93, 31, v92
	v_ashrrev_i32_e32 v91, 31, v90
	v_ashrrev_i32_e32 v101, 31, v100
	v_ashrrev_i32_e32 v99, 31, v98
	v_ashrrev_i32_e32 v105, 31, v104
	v_ashrrev_i32_e32 v103, 31, v102
	v_ashrrev_i32_e32 v109, 31, v108
	v_ashrrev_i32_e32 v107, 31, v106
	v_ashrrev_i32_e32 v113, 31, v112
	v_ashrrev_i32_e32 v111, 31, v110
	v_ashrrev_i32_e32 v117, 31, v116
	v_ashrrev_i32_e32 v115, 31, v114
	v_lshlrev_b64 v[56:57], 12, v[56:57]
	v_lshlrev_b64 v[54:55], 12, v[54:55]
	v_lshlrev_b64 v[58:59], 12, v[58:59]
	v_lshlrev_b64 v[60:61], 12, v[60:61]
	v_lshlrev_b64 v[90:91], 12, v[90:91]
	v_lshlrev_b64 v[92:93], 12, v[92:93]
	v_lshlrev_b64 v[98:99], 12, v[98:99]
	v_lshlrev_b64 v[100:101], 12, v[100:101]
	v_lshlrev_b64 v[102:103], 12, v[102:103]
	v_lshlrev_b64 v[104:105], 12, v[104:105]
	v_lshlrev_b64 v[106:107], 12, v[106:107]
	v_lshlrev_b64 v[108:109], 12, v[108:109]
	v_lshlrev_b64 v[110:111], 12, v[110:111]
	v_lshlrev_b64 v[112:113], 12, v[112:113]
	v_lshlrev_b64 v[114:115], 12, v[114:115]
	v_lshlrev_b64 v[116:117], 12, v[116:117]
	v_lshl_add_u64 v[56:57], v[18:19], 0, v[56:57]
	v_lshl_add_u64 v[54:55], v[18:19], 0, v[54:55]
	v_lshl_add_u64 v[60:61], v[18:19], 0, v[60:61]
	v_lshl_add_u64 v[58:59], v[18:19], 0, v[58:59]
	v_lshl_add_u64 v[92:93], v[18:19], 0, v[92:93]
	v_lshl_add_u64 v[90:91], v[18:19], 0, v[90:91]
	v_lshl_add_u64 v[100:101], v[18:19], 0, v[100:101]
	v_lshl_add_u64 v[98:99], v[18:19], 0, v[98:99]
	v_lshl_add_u64 v[104:105], v[18:19], 0, v[104:105]
	v_lshl_add_u64 v[102:103], v[18:19], 0, v[102:103]
	v_lshl_add_u64 v[108:109], v[18:19], 0, v[108:109]
	v_lshl_add_u64 v[106:107], v[18:19], 0, v[106:107]
	v_lshl_add_u64 v[112:113], v[18:19], 0, v[112:113]
	v_lshl_add_u64 v[110:111], v[18:19], 0, v[110:111]
	v_lshl_add_u64 v[116:117], v[18:19], 0, v[116:117]
	v_lshl_add_u64 v[114:115], v[18:19], 0, v[114:115]
	global_load_dword v51, v[56:57], off
	global_load_dword v53, v[54:55], off
	global_load_dword v62, v[60:61], off
	global_load_dword v82, v[58:59], off
	global_load_dword v86, v[92:93], off
	global_load_dword v89, v[90:91], off
	global_load_dword v118, v[100:101], off
	global_load_dword v119, v[98:99], off
	global_load_dword v120, v[104:105], off
	global_load_dword v121, v[102:103], off
	global_load_dword v122, v[108:109], off
	global_load_dword v123, v[106:107], off
	global_load_dword v124, v[112:113], off
	global_load_dword v125, v[110:111], off
	global_load_dword v126, v[116:117], off
	global_load_dword v127, v[114:115], off
	s_add_i32 s42, s42, 16
	s_add_i32 s7, s7, 16
	s_add_i32 s43, s43, -16
	v_add_u32_e32 v54, s44, v22
	v_add_u32_e32 v56, s45, v1
	v_add_u32_e32 v60, s45, v23
	v_add_u32_e32 v58, s44, v26
	v_add_u32_e32 v92, s45, v27
	v_add_u32_e32 v90, s44, v30
	v_add_u32_e32 v100, s45, v31
	v_add_u32_e32 v98, s44, v34
	v_add_u32_e32 v104, s45, v35
	v_add_u32_e32 v102, s44, v38
	v_add_u32_e32 v108, s45, v39
	v_add_u32_e32 v106, s44, v42
	v_add_u32_e32 v112, s45, v43
	v_add_u32_e32 v110, s44, v46
	v_add_u32_e32 v116, s45, v47
	v_add_u32_e32 v114, s44, v50
	s_cmp_lg_u32 s43, 0
	v_mad_u64_u32 v[54:55], s[44:45], v54, s63, v[20:21]
	v_mad_u64_u32 v[56:57], s[44:45], v56, s63, v[20:21]
	v_mad_u64_u32 v[58:59], s[44:45], v58, s63, v[20:21]
	v_mad_u64_u32 v[60:61], s[44:45], v60, s63, v[20:21]
	v_mad_u64_u32 v[90:91], s[44:45], v90, s63, v[20:21]
	v_mad_u64_u32 v[92:93], s[44:45], v92, s63, v[20:21]
	v_mad_u64_u32 v[98:99], s[44:45], v98, s63, v[20:21]
	v_mad_u64_u32 v[100:101], s[44:45], v100, s63, v[20:21]
	v_mad_u64_u32 v[102:103], s[44:45], v102, s63, v[20:21]
	v_mad_u64_u32 v[104:105], s[44:45], v104, s63, v[20:21]
	v_mad_u64_u32 v[106:107], s[44:45], v106, s63, v[20:21]
	v_mad_u64_u32 v[108:109], s[44:45], v108, s63, v[20:21]
	v_mad_u64_u32 v[110:111], s[44:45], v110, s63, v[20:21]
	v_mad_u64_u32 v[112:113], s[44:45], v112, s63, v[20:21]
	v_mad_u64_u32 v[114:115], s[44:45], v114, s63, v[20:21]
	v_mad_u64_u32 v[116:117], s[44:45], v116, s63, v[20:21]
	s_waitcnt vmcnt(15)
	ds_write_b32 v54, v51
	s_waitcnt vmcnt(14)
	ds_write_b32 v56, v53
	s_waitcnt vmcnt(13)
	ds_write_b32 v58, v62
	s_waitcnt vmcnt(12)
	ds_write_b32 v60, v82
	s_waitcnt vmcnt(11)
	ds_write_b32 v90, v86
	s_waitcnt vmcnt(10)
	ds_write_b32 v92, v89
	s_waitcnt vmcnt(9)
	ds_write_b32 v98, v118
	s_waitcnt vmcnt(8)
	ds_write_b32 v100, v119
	s_waitcnt vmcnt(7)
	ds_write_b32 v102, v120
	s_waitcnt vmcnt(6)
	ds_write_b32 v104, v121
	s_waitcnt vmcnt(5)
	ds_write_b32 v106, v122
	s_waitcnt vmcnt(4)
	ds_write_b32 v108, v123
	s_waitcnt vmcnt(3)
	ds_write_b32 v110, v124
	s_waitcnt vmcnt(2)
	ds_write_b32 v112, v125
	s_waitcnt vmcnt(1)
	ds_write_b32 v114, v126
	s_waitcnt vmcnt(0)
	ds_write_b32 v116, v127
	s_cbranch_scc1 .LBB0_38
	v_lshlrev_b32_e32 v18, 3, v88
	v_ashrrev_i32_e32 v1, 3, v88
	v_and_b32_e32 v20, 56, v18
	s_waitcnt lgkmcnt(0)
	v_mul_u32_u24_e32 v18, 0x84, v20
	v_lshlrev_b32_e32 v19, 2, v1
	v_add3_u32 v30, s62, v18, v19
	s_and_b32 s6, 0xffff, s6
	ds_read2_b32 v[18:19], v30 offset1:33
	s_and_b32 s7, 0xffff, s10
	s_lshl_b32 s6, s6, 1
	s_add_u32 s4, s4, s6
	s_addc_u32 s5, s5, 0
	v_lshlrev_b32_e32 v62, 1, v20
	v_lshl_add_u64 v[20:21], s[4:5], 0, v[62:63]
	v_lshl_add_u64 v[22:23], v[20:21], 0, s[20:21]
	s_waitcnt lgkmcnt(0)
	v_bfe_u32 v20, v18, 16, 1
	v_add3_u32 v18, v18, v20, s64
	ds_read2_b32 v[20:21], v30 offset0:66 offset1:99
	v_bfe_u32 v24, v19, 16, 1
	v_add3_u32 v19, v19, v24, s64
	ds_read2_b32 v[24:25], v30 offset0:132 offset1:165
	v_lshrrev_b32_e32 v18, 16, v18
	v_and_or_b32 v18, v19, s66, v18
	s_waitcnt lgkmcnt(1)
	v_bfe_u32 v19, v20, 16, 1
	v_add3_u32 v19, v20, v19, s64
	v_bfe_u32 v20, v21, 16, 1
	ds_read2_b32 v[26:27], v30 offset0:198 offset1:231
	v_lshrrev_b32_e32 v19, 16, v19
	v_add3_u32 v20, v21, v20, s64
	v_and_or_b32 v19, v20, s66, v19
	s_waitcnt lgkmcnt(1)
	v_bfe_u32 v20, v24, 16, 1
	v_add3_u32 v20, v24, v20, s64
	v_bfe_u32 v21, v25, 16, 1
	v_lshrrev_b32_e32 v20, 16, v20
	v_add3_u32 v21, v25, v21, s64
	v_and_or_b32 v20, v21, s66, v20
	s_waitcnt lgkmcnt(0)
	v_bfe_u32 v21, v26, 16, 1
	v_add3_u32 v21, v26, v21, s64
	v_bfe_u32 v24, v27, 16, 1
	v_lshrrev_b32_e32 v21, 16, v21
	v_add3_u32 v24, v27, v24, s64
	v_and_or_b32 v21, v24, s66, v21
	v_add_u32_e32 v24, s7, v1
	v_ashrrev_i32_e32 v25, 31, v24
	v_lshlrev_b64 v[26:27], 11, v[24:25]
	v_lshl_add_u64 v[26:27], v[22:23], 0, v[26:27]
	global_store_dwordx4 v[26:27], v[18:21], off sc0 sc1
	s_nop 1
	ds_read2_b32 v[18:19], v30 offset0:8 offset1:41
	ds_read2_b32 v[20:21], v30 offset0:74 offset1:107
	ds_read2_b32 v[26:27], v30 offset0:140 offset1:173
	ds_read2_b32 v[28:29], v30 offset0:206 offset1:239
	v_readfirstlane_b32 s10, v150
	s_waitcnt lgkmcnt(3)
	v_bfe_u32 v1, v18, 16, 1
	v_add3_u32 v1, v18, v1, s64
	v_bfe_u32 v18, v19, 16, 1
	v_lshrrev_b32_e32 v1, 16, v1
	v_add3_u32 v18, v19, v18, s64
	v_and_or_b32 v18, v18, s66, v1
	s_waitcnt lgkmcnt(2)
	v_bfe_u32 v1, v20, 16, 1
	v_add3_u32 v1, v20, v1, s64
	v_bfe_u32 v19, v21, 16, 1
	v_lshrrev_b32_e32 v1, 16, v1
	v_add3_u32 v19, v21, v19, s64
	v_and_or_b32 v19, v19, s66, v1
	s_waitcnt lgkmcnt(1)
	v_bfe_u32 v1, v26, 16, 1
	v_add3_u32 v1, v26, v1, s64
	v_bfe_u32 v20, v27, 16, 1
	v_lshrrev_b32_e32 v1, 16, v1
	v_add3_u32 v20, v27, v20, s64
	v_and_or_b32 v20, v20, s66, v1
	s_waitcnt lgkmcnt(0)
	v_bfe_u32 v1, v28, 16, 1
	v_add_u32_e32 v26, 8, v24
	v_add3_u32 v1, v28, v1, s64
	v_bfe_u32 v21, v29, 16, 1
	v_ashrrev_i32_e32 v27, 31, v26
	v_lshrrev_b32_e32 v1, 16, v1
	v_add3_u32 v21, v29, v21, s64
	v_lshlrev_b64 v[26:27], 11, v[26:27]
	v_and_or_b32 v21, v21, s66, v1
	v_lshl_add_u64 v[26:27], v[22:23], 0, v[26:27]
	global_store_dwordx4 v[26:27], v[18:21], off sc0 sc1
	s_nop 1
	ds_read2_b32 v[18:19], v30 offset0:16 offset1:49
	ds_read2_b32 v[20:21], v30 offset0:82 offset1:115
	ds_read2_b32 v[26:27], v30 offset0:148 offset1:181
	ds_read2_b32 v[28:29], v30 offset0:214 offset1:247
	s_waitcnt lgkmcnt(3)
	v_bfe_u32 v1, v18, 16, 1
	v_add3_u32 v1, v18, v1, s64
	v_bfe_u32 v18, v19, 16, 1
	v_lshrrev_b32_e32 v1, 16, v1
	v_add3_u32 v18, v19, v18, s64
	v_and_or_b32 v18, v18, s66, v1
	s_waitcnt lgkmcnt(2)
	v_bfe_u32 v1, v20, 16, 1
	v_add3_u32 v1, v20, v1, s64
	v_bfe_u32 v19, v21, 16, 1
	v_lshrrev_b32_e32 v1, 16, v1
	v_add3_u32 v19, v21, v19, s64
	v_and_or_b32 v19, v19, s66, v1
	s_waitcnt lgkmcnt(1)
	v_bfe_u32 v1, v26, 16, 1
	v_add3_u32 v1, v26, v1, s64
	v_bfe_u32 v20, v27, 16, 1
	v_lshrrev_b32_e32 v1, 16, v1
	v_add3_u32 v20, v27, v20, s64
	v_and_or_b32 v20, v20, s66, v1
	s_waitcnt lgkmcnt(0)
	v_bfe_u32 v1, v28, 16, 1
	v_add_u32_e32 v26, 16, v24
	v_add3_u32 v1, v28, v1, s64
	v_bfe_u32 v21, v29, 16, 1
	v_ashrrev_i32_e32 v27, 31, v26
	v_lshrrev_b32_e32 v1, 16, v1
	v_add3_u32 v21, v29, v21, s64
	v_lshlrev_b64 v[26:27], 11, v[26:27]
	v_and_or_b32 v21, v21, s66, v1
	v_lshl_add_u64 v[26:27], v[22:23], 0, v[26:27]
	global_store_dwordx4 v[26:27], v[18:21], off sc0 sc1
	s_nop 1
	ds_read2_b32 v[18:19], v30 offset0:24 offset1:57
	ds_read2_b32 v[20:21], v30 offset0:90 offset1:123
	ds_read2_b32 v[26:27], v30 offset0:156 offset1:189
	ds_read2_b32 v[28:29], v30 offset0:222 offset1:255
	v_add_u32_e32 v24, 24, v24
	s_waitcnt lgkmcnt(3)
	v_bfe_u32 v1, v18, 16, 1
	v_add3_u32 v1, v18, v1, s64
	v_bfe_u32 v18, v19, 16, 1
	v_lshrrev_b32_e32 v1, 16, v1
	v_add3_u32 v18, v19, v18, s64
	v_and_or_b32 v18, v18, s66, v1
	s_waitcnt lgkmcnt(2)
	v_bfe_u32 v1, v20, 16, 1
	v_add3_u32 v1, v20, v1, s64
	v_bfe_u32 v19, v21, 16, 1
	v_lshrrev_b32_e32 v1, 16, v1
	v_add3_u32 v19, v21, v19, s64
	v_and_or_b32 v19, v19, s66, v1
	s_waitcnt lgkmcnt(1)
	v_bfe_u32 v1, v26, 16, 1
	v_add3_u32 v1, v26, v1, s64
	v_bfe_u32 v20, v27, 16, 1
	v_lshrrev_b32_e32 v1, 16, v1
	v_add3_u32 v20, v27, v20, s64
	v_and_or_b32 v20, v20, s66, v1
	s_waitcnt lgkmcnt(0)
	v_bfe_u32 v1, v28, 16, 1
	v_add3_u32 v1, v28, v1, s64
	v_bfe_u32 v21, v29, 16, 1
	v_ashrrev_i32_e32 v25, 31, v24
	v_lshrrev_b32_e32 v1, 16, v1
	v_add3_u32 v21, v29, v21, s64
	v_lshlrev_b64 v[24:25], 11, v[24:25]
	v_and_or_b32 v21, v21, s66, v1
	v_lshl_add_u64 v[22:23], v[22:23], 0, v[24:25]
	global_store_dwordx4 v[22:23], v[18:21], off sc0 sc1
	s_nop 1
	s_waitcnt lgkmcnt(0)

.LBB0_43:
	s_lshl_b32 s46, s42, 1
	s_lshl_b32 s47, s10, 1
	v_add_u32_e32 v53, s46, v24
	v_add_u32_e32 v51, s47, v21
	v_add_u32_e32 v60, s47, v25
	v_add_u32_e32 v58, s46, v28
	v_add_u32_e32 v62, s47, v29
	v_add_u32_e32 v82, s46, v32
	v_add_u32_e32 v86, s47, v33
	v_add_u32_e32 v89, s46, v36
	v_add_u32_e32 v104, s47, v37
	v_add_u32_e32 v102, s46, v40
	v_add_u32_e32 v108, s47, v41
	v_add_u32_e32 v106, s46, v44
	v_add_u32_e32 v112, s47, v45
	v_add_u32_e32 v110, s46, v48
	v_add_u32_e32 v116, s47, v49
	v_add_u32_e32 v114, s46, v52
	v_mad_i64_i32 v[54:55], s[44:45], v53, s67, v[18:19]
	v_mad_i64_i32 v[56:57], s[44:45], v51, s67, v[18:19]
	v_mad_i64_i32 v[58:59], s[44:45], v58, s67, v[18:19]
	v_mad_i64_i32 v[60:61], s[44:45], v60, s67, v[18:19]
	v_mad_i64_i32 v[90:91], s[44:45], v82, s67, v[18:19]
	v_mad_i64_i32 v[92:93], s[44:45], v62, s67, v[18:19]
	v_mad_i64_i32 v[98:99], s[44:45], v89, s67, v[18:19]
	v_mad_i64_i32 v[100:101], s[44:45], v86, s67, v[18:19]
	v_mad_i64_i32 v[102:103], s[44:45], v102, s67, v[18:19]
	v_mad_i64_i32 v[104:105], s[44:45], v104, s67, v[18:19]
	v_mad_i64_i32 v[106:107], s[44:45], v106, s67, v[18:19]
	v_mad_i64_i32 v[108:109], s[44:45], v108, s67, v[18:19]
	v_mad_i64_i32 v[110:111], s[44:45], v110, s67, v[18:19]
	v_mad_i64_i32 v[112:113], s[44:45], v112, s67, v[18:19]
	v_mad_i64_i32 v[114:115], s[44:45], v114, s67, v[18:19]
	v_mad_i64_i32 v[116:117], s[44:45], v116, s67, v[18:19]
	global_load_dword v51, v[54:55], off
	global_load_dword v53, v[56:57], off
	global_load_dword v62, v[58:59], off
	global_load_dword v82, v[60:61], off
	global_load_dword v86, v[90:91], off
	global_load_dword v89, v[92:93], off
	global_load_dword v118, v[98:99], off
	global_load_dword v119, v[100:101], off
	global_load_dword v120, v[102:103], off
	global_load_dword v121, v[104:105], off
	global_load_dword v122, v[106:107], off
	global_load_dword v123, v[108:109], off
	global_load_dword v124, v[110:111], off
	global_load_dword v125, v[112:113], off
	global_load_dword v126, v[114:115], off
	global_load_dword v127, v[116:117], off
	s_add_i32 s42, s42, 16
	s_add_i32 s10, s10, 16
	s_add_i32 s43, s43, -16
	v_add_u32_e32 v54, s46, v22
	v_add_u32_e32 v56, s47, v1
	v_add_u32_e32 v60, s47, v23
	v_add_u32_e32 v58, s46, v26
	v_add_u32_e32 v92, s47, v27
	v_add_u32_e32 v90, s46, v30
	v_add_u32_e32 v100, s47, v31
	v_add_u32_e32 v98, s46, v34
	v_add_u32_e32 v104, s47, v35
	v_add_u32_e32 v102, s46, v38
	v_add_u32_e32 v108, s47, v39
	v_add_u32_e32 v106, s46, v42
	v_add_u32_e32 v112, s47, v43
	v_add_u32_e32 v110, s46, v46
	v_add_u32_e32 v116, s47, v47
	v_add_u32_e32 v114, s46, v50
	s_cmp_lg_u32 s43, 0
	v_mad_u64_u32 v[54:55], s[44:45], v54, s63, v[20:21]
	v_mad_u64_u32 v[56:57], s[44:45], v56, s63, v[20:21]
	v_mad_u64_u32 v[58:59], s[44:45], v58, s63, v[20:21]
	v_mad_u64_u32 v[60:61], s[44:45], v60, s63, v[20:21]
	v_mad_u64_u32 v[90:91], s[44:45], v90, s63, v[20:21]
	v_mad_u64_u32 v[92:93], s[44:45], v92, s63, v[20:21]
	v_mad_u64_u32 v[98:99], s[44:45], v98, s63, v[20:21]
	v_mad_u64_u32 v[100:101], s[44:45], v100, s63, v[20:21]
	v_mad_u64_u32 v[102:103], s[44:45], v102, s63, v[20:21]
	v_mad_u64_u32 v[104:105], s[44:45], v104, s63, v[20:21]
	v_mad_u64_u32 v[106:107], s[44:45], v106, s63, v[20:21]
	v_mad_u64_u32 v[108:109], s[44:45], v108, s63, v[20:21]
	v_mad_u64_u32 v[110:111], s[44:45], v110, s63, v[20:21]
	v_mad_u64_u32 v[112:113], s[44:45], v112, s63, v[20:21]
	v_mad_u64_u32 v[114:115], s[44:45], v114, s63, v[20:21]
	v_mad_u64_u32 v[116:117], s[44:45], v116, s63, v[20:21]
	s_waitcnt vmcnt(15)
	ds_write_b32 v54, v51
	s_waitcnt vmcnt(14)
	ds_write_b32 v56, v53
	s_waitcnt vmcnt(13)
	ds_write_b32 v58, v62
	s_waitcnt vmcnt(12)
	ds_write_b32 v60, v82
	s_waitcnt vmcnt(11)
	ds_write_b32 v90, v86
	s_waitcnt vmcnt(10)
	ds_write_b32 v92, v89
	s_waitcnt vmcnt(9)
	ds_write_b32 v98, v118
	s_waitcnt vmcnt(8)
	ds_write_b32 v100, v119
	s_waitcnt vmcnt(7)
	ds_write_b32 v102, v120
	s_waitcnt vmcnt(6)
	ds_write_b32 v104, v121
	s_waitcnt vmcnt(5)
	ds_write_b32 v106, v122
	s_waitcnt vmcnt(4)
	ds_write_b32 v108, v123
	s_waitcnt vmcnt(3)
	ds_write_b32 v110, v124
	s_waitcnt vmcnt(2)
	ds_write_b32 v112, v125
	s_waitcnt vmcnt(1)
	ds_write_b32 v114, v126
	s_waitcnt vmcnt(0)
	ds_write_b32 v116, v127
	s_cbranch_scc1 .LBB0_43
	v_lshlrev_b32_e32 v18, 3, v88
	v_ashrrev_i32_e32 v1, 3, v88
	v_and_b32_e32 v20, 56, v18
	s_waitcnt lgkmcnt(0)
	v_mul_u32_u24_e32 v18, 0x84, v20
	v_lshlrev_b32_e32 v19, 2, v1
	v_add3_u32 v28, s62, v18, v19
	s_and_b32 s6, 0xffff, s6
	ds_read2_b32 v[18:19], v28 offset1:33
	s_and_b32 s7, 0xffff, s7
	s_lshl_b32 s6, s6, 1
	s_add_u32 s4, s4, s6
	s_addc_u32 s5, s5, 0
	v_lshlrev_b32_e32 v62, 1, v20
	v_lshl_add_u64 v[20:21], s[4:5], 0, v[62:63]
	v_lshl_add_u64 v[22:23], v[20:21], 0, s[24:25]
	s_waitcnt lgkmcnt(0)
	v_bfe_u32 v20, v18, 16, 1
	v_add3_u32 v18, v18, v20, s64
	ds_read2_b32 v[20:21], v28 offset0:66 offset1:99
	v_bfe_u32 v24, v19, 16, 1
	v_add3_u32 v19, v19, v24, s64
	ds_read2_b32 v[24:25], v28 offset0:132 offset1:165
	v_lshrrev_b32_e32 v18, 16, v18
	v_and_or_b32 v18, v19, s66, v18
	s_waitcnt lgkmcnt(1)
	v_bfe_u32 v19, v20, 16, 1
	v_add3_u32 v19, v20, v19, s64
	v_bfe_u32 v20, v21, 16, 1
	ds_read2_b32 v[26:27], v28 offset0:198 offset1:231
	v_lshrrev_b32_e32 v19, 16, v19
	v_add3_u32 v20, v21, v20, s64
	v_and_or_b32 v19, v20, s66, v19
	s_waitcnt lgkmcnt(1)
	v_bfe_u32 v20, v24, 16, 1
	v_add3_u32 v20, v24, v20, s64
	v_bfe_u32 v21, v25, 16, 1
	v_lshrrev_b32_e32 v20, 16, v20
	v_add3_u32 v21, v25, v21, s64
	v_and_or_b32 v20, v21, s66, v20
	s_waitcnt lgkmcnt(0)
	v_bfe_u32 v21, v26, 16, 1
	v_add3_u32 v21, v26, v21, s64
	v_bfe_u32 v24, v27, 16, 1
	v_lshrrev_b32_e32 v21, 16, v21
	v_add3_u32 v24, v27, v24, s64
	v_and_or_b32 v21, v24, s66, v21
	v_add_u32_e32 v24, s7, v1
	v_lshlrev_b32_e32 v25, 1, v1
	v_lshrrev_b32_e32 v26, 3, v24
	v_and_b32_e32 v25, 56, v25
	v_and_b32_e32 v26, 4, v26
	v_and_b32_e32 v27, 0xffffffc3, v24
	v_or3_b32 v25, v27, v25, v26
	v_cmp_gt_i32_e32 vcc, s68, v24
	v_add_u32_e32 v29, 8, v1
	v_readfirstlane_b32 s10, v150
	v_cndmask_b32_e32 v24, v24, v25, vcc
	v_ashrrev_i32_e32 v25, 31, v24
	v_lshlrev_b64 v[24:25], 11, v[24:25]
	v_lshl_add_u64 v[24:25], v[22:23], 0, v[24:25]
	global_store_dwordx4 v[24:25], v[18:21], off sc0 sc1
	s_nop 1
	ds_read2_b32 v[18:19], v28 offset0:8 offset1:41
	ds_read2_b32 v[26:27], v28 offset0:206 offset1:239
	s_waitcnt lgkmcnt(1)
	v_bfe_u32 v20, v18, 16, 1
	v_add3_u32 v18, v18, v20, s64
	ds_read2_b32 v[20:21], v28 offset0:74 offset1:107
	v_bfe_u32 v24, v19, 16, 1
	v_add3_u32 v19, v19, v24, s64
	ds_read2_b32 v[24:25], v28 offset0:140 offset1:173
	v_lshrrev_b32_e32 v18, 16, v18
	v_and_or_b32 v18, v19, s66, v18
	s_waitcnt lgkmcnt(1)
	v_bfe_u32 v19, v20, 16, 1
	v_add3_u32 v19, v20, v19, s64
	v_bfe_u32 v20, v21, 16, 1
	v_lshrrev_b32_e32 v19, 16, v19
	v_add3_u32 v20, v21, v20, s64
	v_and_or_b32 v19, v20, s66, v19
	s_waitcnt lgkmcnt(0)
	v_bfe_u32 v20, v24, 16, 1
	v_add3_u32 v20, v24, v20, s64
	v_bfe_u32 v21, v25, 16, 1
	v_lshrrev_b32_e32 v20, 16, v20
	v_add3_u32 v21, v25, v21, s64
	v_and_or_b32 v20, v21, s66, v20
	v_bfe_u32 v21, v26, 16, 1
	v_add3_u32 v21, v26, v21, s64
	v_bfe_u32 v24, v27, 16, 1
	v_lshrrev_b32_e32 v21, 16, v21
	v_add3_u32 v24, v27, v24, s64
	v_and_or_b32 v21, v24, s66, v21
	v_add_u32_e32 v24, s7, v29
	v_lshlrev_b32_e32 v25, 1, v29
	v_lshrrev_b32_e32 v26, 3, v24
	v_and_b32_e32 v25, 56, v25
	v_and_b32_e32 v26, 4, v26
	v_and_b32_e32 v27, 0xffffffc3, v24
	v_or3_b32 v25, v27, v25, v26
	v_cmp_gt_i32_e32 vcc, s68, v24
	v_add_u32_e32 v29, 16, v1
	v_add_u32_e32 v1, 24, v1
	v_cndmask_b32_e32 v24, v24, v25, vcc
	v_ashrrev_i32_e32 v25, 31, v24
	v_lshlrev_b64 v[24:25], 11, v[24:25]
	v_lshl_add_u64 v[24:25], v[22:23], 0, v[24:25]
	global_store_dwordx4 v[24:25], v[18:21], off sc0 sc1
	s_nop 1
	ds_read2_b32 v[18:19], v28 offset0:16 offset1:49
	ds_read2_b32 v[26:27], v28 offset0:214 offset1:247
	s_waitcnt lgkmcnt(1)
	v_bfe_u32 v20, v18, 16, 1
	v_add3_u32 v18, v18, v20, s64
	ds_read2_b32 v[20:21], v28 offset0:82 offset1:115
	v_bfe_u32 v24, v19, 16, 1
	v_add3_u32 v19, v19, v24, s64
	ds_read2_b32 v[24:25], v28 offset0:148 offset1:181
	v_lshrrev_b32_e32 v18, 16, v18
	v_and_or_b32 v18, v19, s66, v18
	s_waitcnt lgkmcnt(1)
	v_bfe_u32 v19, v20, 16, 1
	v_add3_u32 v19, v20, v19, s64
	v_bfe_u32 v20, v21, 16, 1
	v_lshrrev_b32_e32 v19, 16, v19
	v_add3_u32 v20, v21, v20, s64
	v_and_or_b32 v19, v20, s66, v19
	s_waitcnt lgkmcnt(0)
	v_bfe_u32 v20, v24, 16, 1
	v_add3_u32 v20, v24, v20, s64
	v_bfe_u32 v21, v25, 16, 1
	v_lshrrev_b32_e32 v20, 16, v20
	v_add3_u32 v21, v25, v21, s64
	v_and_or_b32 v20, v21, s66, v20
	v_bfe_u32 v21, v26, 16, 1
	v_add3_u32 v21, v26, v21, s64
	v_bfe_u32 v24, v27, 16, 1
	v_lshrrev_b32_e32 v21, 16, v21
	v_add3_u32 v24, v27, v24, s64
	v_and_or_b32 v21, v24, s66, v21
	v_add_u32_e32 v24, s7, v29
	v_lshlrev_b32_e32 v25, 1, v29
	v_lshrrev_b32_e32 v26, 3, v24
	v_and_b32_e32 v25, 56, v25
	v_and_b32_e32 v26, 4, v26
	v_and_b32_e32 v27, 0xffffffc3, v24
	v_or3_b32 v25, v27, v25, v26
	v_cmp_gt_i32_e32 vcc, s68, v24
	s_nop 1
	v_cndmask_b32_e32 v24, v24, v25, vcc
	v_ashrrev_i32_e32 v25, 31, v24
	v_lshlrev_b64 v[24:25], 11, v[24:25]
	v_lshl_add_u64 v[24:25], v[22:23], 0, v[24:25]
	global_store_dwordx4 v[24:25], v[18:21], off sc0 sc1
	s_nop 1
	ds_read2_b32 v[18:19], v28 offset0:24 offset1:57
	ds_read2_b32 v[26:27], v28 offset0:222 offset1:255
	s_waitcnt lgkmcnt(1)
	v_bfe_u32 v20, v18, 16, 1
	v_add3_u32 v18, v18, v20, s64
	ds_read2_b32 v[20:21], v28 offset0:90 offset1:123
	v_bfe_u32 v24, v19, 16, 1
	v_add3_u32 v19, v19, v24, s64
	ds_read2_b32 v[24:25], v28 offset0:156 offset1:189
	v_lshrrev_b32_e32 v18, 16, v18
	v_and_or_b32 v18, v19, s66, v18
	s_waitcnt lgkmcnt(1)
	v_bfe_u32 v19, v20, 16, 1
	v_add3_u32 v19, v20, v19, s64
	v_bfe_u32 v20, v21, 16, 1
	v_lshrrev_b32_e32 v19, 16, v19
	v_add3_u32 v20, v21, v20, s64
	v_and_or_b32 v19, v20, s66, v19
	s_waitcnt lgkmcnt(0)
	v_bfe_u32 v20, v24, 16, 1
	v_add3_u32 v20, v24, v20, s64
	v_bfe_u32 v21, v25, 16, 1
	v_lshrrev_b32_e32 v20, 16, v20
	v_add3_u32 v21, v25, v21, s64
	v_and_or_b32 v20, v21, s66, v20
	v_bfe_u32 v21, v26, 16, 1
	v_add3_u32 v21, v26, v21, s64
	v_bfe_u32 v24, v27, 16, 1
	v_lshrrev_b32_e32 v21, 16, v21
	v_add3_u32 v24, v27, v24, s64
	v_and_or_b32 v21, v24, s66, v21
	v_add_u32_e32 v24, s7, v1
	v_lshlrev_b32_e32 v1, 1, v1
	v_lshrrev_b32_e32 v25, 3, v24
	v_and_b32_e32 v1, 56, v1
	v_and_b32_e32 v25, 4, v25
	v_and_b32_e32 v26, 0xffffffc3, v24
	v_or3_b32 v1, v26, v1, v25
	v_cmp_gt_i32_e32 vcc, s68, v24
	s_nop 1
	v_cndmask_b32_e32 v24, v24, v1, vcc
	v_ashrrev_i32_e32 v25, 31, v24
	v_lshlrev_b64 v[24:25], 11, v[24:25]
	v_lshl_add_u64 v[22:23], v[22:23], 0, v[24:25]
	global_store_dwordx4 v[22:23], v[18:21], off sc0 sc1
	s_nop 1
	s_waitcnt lgkmcnt(0)

.LBB0_46:
	s_andn2_b64 vcc, exec, s[4:5]
	s_cbranch_vccnz .LBB0_48
	s_lshl_b32 s5, s40, 2
	s_add_i32 s4, s5, 0xfffffc00
	s_add_i32 s42, s5, 0xfffffc02
	s_add_i32 s10, s5, 0xfffffc03
	s_add_i32 s6, s5, 0xffff7c03
	s_cmpk_lt_u32 s4, 0x8000
	s_cselect_b32 s44, s10, s6
	s_cselect_b32 s45, 0, 0
	s_add_i32 s6, s5, 0xffff7c02
	s_cmpk_lt_u32 s4, 0x8000
	s_cselect_b32 s7, 0, 8
	s_cselect_b32 s47, 0, 0
	s_cselect_b32 s46, s42, s6
	s_add_i32 s6, s5, 0xfffffc01
	s_add_i32 s43, s5, 0xffff7c01
	s_cmpk_lt_u32 s4, 0x8000
	s_cselect_b32 s48, s6, s43
	s_cselect_b32 s49, 0, 0
	s_add_i32 s5, s5, 0xffff7c00
	s_cmpk_lt_u32 s40, 0x2100
	s_cselect_b32 s56, s4, s5
	s_cselect_b32 s5, 0, 8
	s_cselect_b32 s57, 0, 0
	s_add_u32 s50, s8, s5
	s_addc_u32 s51, s9, 0
	s_load_dwordx2 s[50:51], s[50:51], 0x0
	s_lshl_b64 s[58:59], s[56:57], 12
	v_ashrrev_i32_e32 v89, 31, v88
	s_load_dwordx2 s[60:61], s[8:9], 0xc0
	v_lshlrev_b64 v[34:35], 4, v[88:89]
	s_waitcnt lgkmcnt(0)
	s_add_u32 s50, s50, s58
	s_addc_u32 s51, s51, s59
	v_lshl_add_u64 v[26:27], s[50:51], 0, v[34:35]
	global_load_dwordx4 v[30:33], v[26:27], off
	global_load_dwordx4 v[22:25], v[26:27], off offset:1024
	global_load_dwordx4 v[18:21], v[26:27], off offset:3072
	s_nop 0
	global_load_dwordx4 v[26:29], v[26:27], off offset:2048
	v_and_b32_e32 v1, 64, v96
	v_xor_b32_e32 v36, 1, v96
	v_add_u32_e32 v50, 64, v1
	v_xor_b32_e32 v37, 2, v96
	v_cmp_lt_i32_e32 vcc, v36, v50
	v_xor_b32_e32 v38, 4, v96
	v_xor_b32_e32 v39, 8, v96
	v_cndmask_b32_e32 v1, v96, v36, vcc
	v_cmp_lt_i32_e32 vcc, v37, v50
	v_xor_b32_e32 v40, 16, v96
	v_xor_b32_e32 v47, 32, v96
	v_cndmask_b32_e32 v51, v96, v37, vcc
	v_cmp_lt_i32_e32 vcc, v38, v50
	s_add_u32 s50, s8, s7
	s_addc_u32 s51, s9, 0
	v_cndmask_b32_e32 v52, v96, v38, vcc
	v_cmp_lt_i32_e32 vcc, v39, v50
	v_lshlrev_b32_e32 v1, 2, v1
	s_load_dwordx2 s[50:51], s[50:51], 0x0
	v_cndmask_b32_e32 v53, v96, v39, vcc
	v_cmp_lt_i32_e32 vcc, v40, v50
	s_lshl_b64 s[48:49], s[48:49], 12
	v_lshlrev_b32_e32 v93, 2, v51
	v_cndmask_b32_e32 v54, v96, v40, vcc
	s_waitcnt lgkmcnt(0)
	s_add_u32 s48, s50, s48
	s_addc_u32 s49, s51, s49
	v_lshlrev_b32_e32 v82, 2, v54
	v_cmp_lt_i32_e32 vcc, v47, v50
	v_lshlrev_b32_e32 v92, 2, v52
	v_lshlrev_b32_e32 v86, 2, v53
	s_lshl_b64 s[46:47], s[46:47], 12
	s_add_u32 s46, s50, s46
	s_addc_u32 s47, s51, s47
	s_lshl_b64 s[44:45], s[44:45], 12
	s_mov_b32 s5, s11
	s_add_u32 s44, s50, s44
	s_addc_u32 s45, s51, s45
	v_lshl_add_u64 v[102:103], s[44:45], 0, v[34:35]
	s_mov_b32 s7, s11
	s_mov_b32 s43, s11
	s_waitcnt vmcnt(3)
	v_pk_mul_f32 v[36:37], v[32:33], v[32:33]
	v_pk_mul_f32 v[38:39], v[30:31], v[30:31]
	s_waitcnt vmcnt(2)
	v_pk_mul_f32 v[40:41], v[24:25], v[24:25]
	v_pk_mul_f32 v[42:43], v[22:23], v[22:23]
	v_pk_mov_b32 v[48:49], v[38:39], v[36:37] op_sel:[1,0]
	v_mov_b32_e32 v39, v37
	v_pk_mov_b32 v[36:37], v[42:43], v[40:41] op_sel:[1,0]
	v_mov_b32_e32 v43, v41
	s_waitcnt vmcnt(0)
	v_mul_f32_e32 v44, v27, v27
	v_mul_f32_e32 v46, v29, v29
	v_pk_add_f32 v[38:39], v[48:49], v[38:39]
	v_pk_add_f32 v[36:37], v[36:37], v[42:43]
	v_mul_f32_e32 v55, v18, v18
	v_mul_f32_e32 v56, v19, v19
	v_mul_f32_e32 v57, v20, v20
	v_mul_f32_e32 v58, v21, v21
	v_pk_fma_f32 v[40:41], v[26:27], v[26:27], v[44:45] op_sel_hi:[1,1,0]
	v_pk_fma_f32 v[44:45], v[28:29], v[28:29], v[46:47] op_sel_hi:[1,1,0]
	v_pk_add_f32 v[38:39], v[38:39], v[38:39] op_sel:[0,1] op_sel_hi:[1,0]
	v_pk_add_f32 v[36:37], v[36:37], v[36:37] op_sel:[0,1] op_sel_hi:[1,0]
	v_mov_b32_e32 v41, v57
	v_mov_b32_e32 v45, v58
	v_mov_b32_e32 v39, v55
	v_mov_b32_e32 v37, v56
	v_pk_add_f32 v[40:41], v[40:41], v[44:45]
	v_pk_add_f32 v[36:37], v[38:39], v[36:37]
	v_cndmask_b32_e32 v38, v96, v47, vcc
	v_pk_add_f32 v[36:37], v[36:37], v[40:41]
	v_lshlrev_b32_e32 v62, 2, v38
	v_add_f32_e32 v36, v36, v37
	ds_bpermute_b32 v37, v1, v36
	s_waitcnt lgkmcnt(0)
	v_add_f32_e32 v39, v36, v37
	v_lshl_add_u64 v[36:37], v[88:89], 3, s[60:61]
	v_lshl_add_u64 v[90:91], v[36:37], 0, s[26:27]
	v_lshl_add_u64 v[36:37], s[48:49], 0, v[34:35]
	global_load_dwordx4 v[98:101], v[36:37], off
	global_load_dwordx4 v[54:57], v[36:37], off offset:1024
	global_load_dwordx4 v[50:53], v[36:37], off offset:3072
	global_load_dwordx4 v[58:61], v[36:37], off offset:2048
	ds_bpermute_b32 v40, v93, v39
	v_lshl_add_u64 v[36:37], s[46:47], 0, v[34:35]
	s_lshl_b64 s[46:47], s[4:5], 11
	s_waitcnt lgkmcnt(0)
	v_add_f32_e32 v38, v39, v40
	ds_bpermute_b32 v39, v92, v38
	s_waitcnt lgkmcnt(0)
	v_add_f32_e32 v38, v38, v39
	ds_bpermute_b32 v39, v86, v38
	s_waitcnt lgkmcnt(0)
	v_add_f32_e32 v38, v38, v39
	ds_bpermute_b32 v39, v82, v38
	s_waitcnt lgkmcnt(0)
	v_add_f32_e32 v38, v38, v39
	ds_bpermute_b32 v39, v62, v38
	s_waitcnt lgkmcnt(0)
	v_add_f32_e32 v38, v38, v39
	v_fmamk_f32 v38, v38, 0x3a800000, v94
	v_mul_f32_e32 v39, 0x4f800000, v38
	v_cmp_gt_f32_e32 vcc, s69, v38
	s_nop 1
	v_cndmask_b32_e32 v38, v38, v39, vcc
	v_sqrt_f32_e32 v39, v38
	s_nop 0
	v_add_u32_e32 v40, -1, v39
	v_add_u32_e32 v41, 1, v39
	v_fma_f32 v42, -v40, v39, v38
	v_fma_f32 v43, -v41, v39, v38
	v_cmp_ge_f32_e64 s[4:5], 0, v42
	s_nop 1
	v_cndmask_b32_e64 v39, v39, v40, s[4:5]
	v_cmp_lt_f32_e64 s[4:5], 0, v43
	s_nop 1
	v_cndmask_b32_e64 v39, v39, v41, s[4:5]
	v_mul_f32_e32 v40, 0x37800000, v39
	v_cndmask_b32_e32 v39, v39, v40, vcc
	v_cmp_class_f32_e32 vcc, v38, v95
	s_nop 1
	v_cndmask_b32_e32 v38, v39, v38, vcc
	v_div_scale_f32 v39, s[4:5], v38, v38, 1.0
	v_rcp_f32_e32 v40, v39
	v_div_scale_f32 v34, vcc, 1.0, v38, 1.0
	v_fma_f32 v35, -v39, v40, 1.0
	v_fmac_f32_e32 v40, v35, v40
	v_mul_f32_e32 v35, v34, v40
	v_fma_f32 v41, -v39, v35, v34
	v_fmac_f32_e32 v35, v41, v40
	v_fma_f32 v34, -v39, v35, v34
	v_div_fmas_f32 v34, v34, v40, v35
	v_div_fixup_f32 v34, v34, v38, 1.0
	v_pk_mul_f32 v[30:31], v[30:31], v[34:35] op_sel_hi:[1,0]
	v_pk_mul_f32 v[32:33], v[32:33], v[34:35] op_sel_hi:[1,0]
	v_pk_mul_f32 v[112:113], v[18:19], v[34:35] op_sel_hi:[1,0]
	v_pk_mul_f32 v[114:115], v[20:21], v[34:35] op_sel_hi:[1,0]
	v_pk_mul_f32 v[18:19], v[4:5], v[32:33]
	v_pk_mul_f32 v[20:21], v[2:3], v[30:31]
	v_pk_mul_f32 v[104:105], v[22:23], v[34:35] op_sel_hi:[1,0]
	v_pk_mul_f32 v[106:107], v[24:25], v[34:35] op_sel_hi:[1,0]
	v_bfe_u32 v22, v20, 16, 1
	v_bfe_u32 v24, v18, 16, 1
	v_bfe_u32 v23, v21, 16, 1
	v_bfe_u32 v25, v19, 16, 1
	v_add3_u32 v20, v20, v22, s64
	v_add3_u32 v18, v18, v24, s64
	v_pk_mul_f32 v[104:105], v[6:7], v[104:105]
	v_add3_u32 v21, v21, v23, s64
	v_add3_u32 v19, v19, v25, s64
	v_lshrrev_b32_e32 v20, 16, v20
	v_lshrrev_b32_e32 v18, 16, v18
	v_bfe_u32 v89, v104, 16, 1
	v_pk_mul_f32 v[108:109], v[26:27], v[34:35] op_sel_hi:[1,0]
	v_pk_mul_f32 v[110:111], v[28:29], v[34:35] op_sel_hi:[1,0]
	v_and_or_b32 v116, v21, s66, v20
	v_and_or_b32 v117, v19, s66, v18
	global_load_dwordx4 v[46:49], v[36:37], off
	global_load_dwordx4 v[42:45], v[36:37], off offset:1024
	global_load_dwordx4 v[38:41], v[36:37], off offset:2048
	s_nop 0
	global_load_dwordx4 v[34:37], v[36:37], off offset:3072
	s_nop 0
	global_load_dwordx4 v[30:33], v[102:103], off
	global_load_dwordx4 v[26:29], v[102:103], off offset:1024
	global_load_dwordx4 v[22:25], v[102:103], off offset:2048
	global_load_dwordx4 v[18:21], v[102:103], off offset:3072
	v_lshl_add_u64 v[102:103], v[90:91], 0, s[46:47]
	v_add3_u32 v89, v104, v89, s64
	v_bfe_u32 v104, v105, 16, 1
	global_store_dwordx2 v[102:103], v[116:117], off sc1
	v_add3_u32 v116, v105, v104, s64
	v_pk_mul_f32 v[104:105], v[8:9], v[106:107]
	v_lshrrev_b32_e32 v89, 16, v89
	v_bfe_u32 v106, v104, 16, 1
	v_add3_u32 v106, v104, v106, s64
	v_bfe_u32 v104, v105, 16, 1
	v_add3_u32 v105, v105, v104, s64
	v_and_or_b32 v104, v116, s66, v89
	v_lshrrev_b32_e32 v89, 16, v106
	v_and_or_b32 v105, v105, s66, v89
	global_store_dwordx2 v[102:103], v[104:105], off offset:512 sc1
	s_waitcnt vmcnt(13)
	v_pk_mul_f32 v[104:105], v[100:101], v[100:101]
	v_pk_mul_f32 v[106:107], v[98:99], v[98:99]
	s_nop 0
	v_pk_mov_b32 v[116:117], v[106:107], v[104:105] op_sel:[1,0]
	v_mov_b32_e32 v107, v105
	v_pk_add_f32 v[104:105], v[116:117], v[106:107]
	s_waitcnt vmcnt(12)
	v_pk_mul_f32 v[106:107], v[56:57], v[56:57]
	v_pk_mul_f32 v[116:117], v[54:55], v[54:55]
	v_pk_add_f32 v[104:105], v[104:105], v[104:105] op_sel:[0,1] op_sel_hi:[1,0]
	v_pk_mov_b32 v[118:119], v[116:117], v[106:107] op_sel:[1,0]
	v_mov_b32_e32 v117, v107
	v_pk_add_f32 v[106:107], v[118:119], v[116:117]
	s_waitcnt vmcnt(11)
	v_mul_f32_e32 v105, v50, v50
	v_pk_add_f32 v[106:107], v[106:107], v[106:107] op_sel:[0,1] op_sel_hi:[1,0]
	s_waitcnt vmcnt(10)
	v_mul_f32_e32 v116, v61, v61
	v_mul_f32_e32 v107, v51, v51
	v_pk_add_f32 v[104:105], v[104:105], v[106:107]
	v_mul_f32_e32 v106, v59, v59
	v_pk_fma_f32 v[106:107], v[58:59], v[58:59], v[106:107] op_sel_hi:[1,1,0]
	v_pk_fma_f32 v[116:117], v[60:61], v[60:61], v[116:117] op_sel_hi:[1,1,0]
	v_mul_f32_e32 v107, v52, v52
	v_mul_f32_e32 v117, v53, v53
	v_pk_add_f32 v[106:107], v[106:107], v[116:117]
	s_nop 0
	v_pk_add_f32 v[104:105], v[104:105], v[106:107]
	s_nop 0
	v_add_f32_e32 v89, v104, v105
	ds_bpermute_b32 v106, v1, v89
	v_pk_mul_f32 v[104:105], v[10:11], v[108:109]
	s_waitcnt lgkmcnt(0)
	v_add_f32_e32 v89, v89, v106
	ds_bpermute_b32 v106, v93, v89
	v_bfe_u32 v107, v104, 16, 1
	v_add3_u32 v107, v104, v107, s64
	v_bfe_u32 v104, v105, 16, 1
	v_add3_u32 v108, v105, v104, s64
	s_waitcnt lgkmcnt(0)
	v_add_f32_e32 v89, v89, v106
	ds_bpermute_b32 v106, v92, v89
	v_pk_mul_f32 v[104:105], v[12:13], v[110:111]
	s_waitcnt lgkmcnt(0)
	v_add_f32_e32 v89, v89, v106
	ds_bpermute_b32 v106, v86, v89
	v_bfe_u32 v109, v104, 16, 1
	v_add3_u32 v109, v104, v109, s64
	v_bfe_u32 v104, v105, 16, 1
	v_add3_u32 v105, v105, v104, s64
	s_waitcnt lgkmcnt(0)
	v_add_f32_e32 v89, v89, v106
	ds_bpermute_b32 v106, v82, v89
	v_lshrrev_b32_e32 v104, 16, v107
	v_lshrrev_b32_e32 v107, 16, v109
	v_and_or_b32 v104, v108, s66, v104
	v_and_or_b32 v105, v105, s66, v107
	s_waitcnt lgkmcnt(0)
	v_add_f32_e32 v89, v89, v106
	ds_bpermute_b32 v106, v62, v89
	global_store_dwordx2 v[102:103], v[104:105], off offset:1024 sc1
	v_pk_mul_f32 v[104:105], v[14:15], v[112:113]
	s_waitcnt lgkmcnt(0)
	v_add_f32_e32 v89, v89, v106
	v_fmamk_f32 v89, v89, 0x3a800000, v94
	v_mul_f32_e32 v106, 0x4f800000, v89
	v_cmp_gt_f32_e32 vcc, s69, v89
	v_bfe_u32 v107, v104, 16, 1
	v_add3_u32 v107, v104, v107, s64
	v_cndmask_b32_e32 v89, v89, v106, vcc
	v_bfe_u32 v104, v105, 16, 1
	v_sqrt_f32_e32 v106, v89
	v_add3_u32 v108, v105, v104, s64
	v_pk_mul_f32 v[104:105], v[16:17], v[114:115]
	s_nop 0
	v_bfe_u32 v109, v104, 16, 1
	v_add3_u32 v109, v104, v109, s64
	v_bfe_u32 v104, v105, 16, 1
	v_add3_u32 v105, v105, v104, s64
	v_lshrrev_b32_e32 v104, 16, v107
	v_add_u32_e32 v107, -1, v106
	v_and_or_b32 v104, v108, s66, v104
	v_fma_f32 v108, -v107, v106, v89
	v_cmp_ge_f32_e64 s[4:5], 0, v108
	v_add_u32_e32 v108, 1, v106
	s_nop 0
	v_cndmask_b32_e64 v107, v106, v107, s[4:5]
	v_fma_f32 v106, -v108, v106, v89
	v_cmp_lt_f32_e64 s[4:5], 0, v106
	s_nop 1
	v_cndmask_b32_e64 v106, v107, v108, s[4:5]
	v_mul_f32_e32 v107, 0x37800000, v106
	v_cndmask_b32_e32 v106, v106, v107, vcc
	v_cmp_class_f32_e32 vcc, v89, v95
	v_lshrrev_b32_e32 v108, 16, v109
	v_and_or_b32 v105, v105, s66, v108
	v_cndmask_b32_e32 v89, v106, v89, vcc
	v_div_scale_f32 v106, s[4:5], v89, v89, 1.0
	v_rcp_f32_e32 v107, v106
	global_store_dwordx2 v[102:103], v[104:105], off offset:1536 sc1
	s_lshl_b64 s[4:5], s[6:7], 11
	v_fma_f32 v102, -v106, v107, 1.0
	v_fmac_f32_e32 v107, v102, v107
	v_div_scale_f32 v102, vcc, 1.0, v89, 1.0
	v_mul_f32_e32 v103, v102, v107
	v_fma_f32 v104, -v106, v103, v102
	v_fmac_f32_e32 v103, v104, v107
	v_fma_f32 v102, -v106, v103, v102
	v_div_fmas_f32 v102, v102, v107, v103
	v_div_fixup_f32 v102, v102, v89, 1.0
	v_pk_mul_f32 v[98:99], v[98:99], v[102:103] op_sel_hi:[1,0]
	v_pk_mul_f32 v[100:101], v[100:101], v[102:103] op_sel_hi:[1,0]
	v_pk_mul_f32 v[98:99], v[2:3], v[98:99]
	v_pk_mul_f32 v[54:55], v[54:55], v[102:103] op_sel_hi:[1,0]
	v_bfe_u32 v89, v98, 16, 1
	v_add3_u32 v89, v98, v89, s64
	v_bfe_u32 v98, v99, 16, 1
	v_pk_mul_f32 v[56:57], v[56:57], v[102:103] op_sel_hi:[1,0]
	v_pk_mul_f32 v[58:59], v[58:59], v[102:103] op_sel_hi:[1,0]
	v_pk_mul_f32 v[60:61], v[60:61], v[102:103] op_sel_hi:[1,0]
	v_pk_mul_f32 v[50:51], v[50:51], v[102:103] op_sel_hi:[1,0]
	v_pk_mul_f32 v[52:53], v[52:53], v[102:103] op_sel_hi:[1,0]
	v_add3_u32 v102, v99, v98, s64
	v_pk_mul_f32 v[98:99], v[4:5], v[100:101]
	v_lshrrev_b32_e32 v89, 16, v89
	v_bfe_u32 v100, v98, 16, 1
	v_add3_u32 v100, v98, v100, s64
	v_bfe_u32 v98, v99, 16, 1
	v_add3_u32 v99, v99, v98, s64
	v_and_or_b32 v98, v102, s66, v89
	v_lshrrev_b32_e32 v89, 16, v100
	v_pk_mul_f32 v[54:55], v[6:7], v[54:55]
	v_and_or_b32 v99, v99, s66, v89
	v_bfe_u32 v89, v54, 16, 1
	v_lshl_add_u64 v[100:101], v[90:91], 0, s[4:5]
	v_add3_u32 v89, v54, v89, s64
	v_bfe_u32 v54, v55, 16, 1
	global_store_dwordx2 v[100:101], v[98:99], off sc1
	v_add3_u32 v98, v55, v54, s64
	v_pk_mul_f32 v[54:55], v[8:9], v[56:57]
	v_pk_mul_f32 v[50:51], v[14:15], v[50:51]
	v_bfe_u32 v56, v54, 16, 1
	v_add3_u32 v56, v54, v56, s64
	v_bfe_u32 v54, v55, 16, 1
	v_add3_u32 v55, v55, v54, s64
	v_lshrrev_b32_e32 v54, 16, v89
	v_lshrrev_b32_e32 v56, 16, v56
	v_and_or_b32 v54, v98, s66, v54
	v_and_or_b32 v55, v55, s66, v56
	global_store_dwordx2 v[100:101], v[54:55], off offset:512 sc1
	v_pk_mul_f32 v[54:55], v[10:11], v[58:59]
	s_waitcnt vmcnt(13)
	v_pk_mul_f32 v[58:59], v[46:47], v[46:47]
	v_bfe_u32 v56, v54, 16, 1
	v_add3_u32 v89, v54, v56, s64
	v_pk_mul_f32 v[56:57], v[48:49], v[48:49]
	s_waitcnt vmcnt(11)
	v_mul_f32_e32 v54, v39, v39
	v_pk_mov_b32 v[98:99], v[58:59], v[56:57] op_sel:[1,0]
	v_mov_b32_e32 v59, v57
	v_pk_add_f32 v[56:57], v[98:99], v[58:59]
	v_pk_mul_f32 v[58:59], v[44:45], v[44:45]
	v_pk_mul_f32 v[98:99], v[42:43], v[42:43]
	v_pk_add_f32 v[56:57], v[56:57], v[56:57] op_sel:[0,1] op_sel_hi:[1,0]
	v_pk_mov_b32 v[102:103], v[98:99], v[58:59] op_sel:[1,0]
	v_mov_b32_e32 v99, v59
	v_pk_add_f32 v[58:59], v[102:103], v[98:99]
	s_waitcnt vmcnt(10)
	v_mul_f32_e32 v57, v34, v34
	v_pk_add_f32 v[58:59], v[58:59], v[58:59] op_sel:[0,1] op_sel_hi:[1,0]
	v_bfe_u32 v104, v55, 16, 1
	v_mul_f32_e32 v59, v35, v35
	v_pk_add_f32 v[56:57], v[56:57], v[58:59]
	v_pk_fma_f32 v[58:59], v[38:39], v[38:39], v[54:55] op_sel_hi:[1,1,0]
	v_mul_f32_e32 v54, v41, v41
	v_pk_fma_f32 v[98:99], v[40:41], v[40:41], v[54:55] op_sel_hi:[1,1,0]
	v_mul_f32_e32 v59, v36, v36
	v_mul_f32_e32 v99, v37, v37
	v_pk_add_f32 v[58:59], v[58:59], v[98:99]
	s_nop 0
	v_pk_add_f32 v[56:57], v[56:57], v[58:59]
	v_add3_u32 v58, v55, v104, s64
	v_add_f32_e32 v56, v56, v57
	ds_bpermute_b32 v57, v1, v56
	v_pk_mul_f32 v[54:55], v[12:13], v[60:61]
	s_waitcnt lgkmcnt(0)
	v_add_f32_e32 v56, v56, v57
	ds_bpermute_b32 v57, v93, v56
	v_bfe_u32 v59, v54, 16, 1
	v_add3_u32 v59, v54, v59, s64
	v_bfe_u32 v54, v55, 16, 1
	v_add3_u32 v55, v55, v54, s64
	s_waitcnt lgkmcnt(0)
	v_add_f32_e32 v56, v56, v57
	ds_bpermute_b32 v57, v92, v56
	v_lshrrev_b32_e32 v54, 16, v89
	v_and_or_b32 v54, v58, s66, v54
	v_lshrrev_b32_e32 v58, 16, v59
	v_and_or_b32 v55, v55, s66, v58
	global_store_dwordx2 v[100:101], v[54:55], off offset:1024 sc1
	s_waitcnt lgkmcnt(0)
	v_add_f32_e32 v54, v56, v57
	ds_bpermute_b32 v55, v86, v54
	v_bfe_u32 v56, v50, 16, 1
	v_add3_u32 v56, v50, v56, s64
	v_bfe_u32 v50, v51, 16, 1
	v_add3_u32 v57, v51, v50, s64
	s_waitcnt lgkmcnt(0)
	v_add_f32_e32 v54, v54, v55
	ds_bpermute_b32 v55, v82, v54
	v_pk_mul_f32 v[50:51], v[16:17], v[52:53]
	s_waitcnt lgkmcnt(0)
	v_add_f32_e32 v53, v54, v55
	ds_bpermute_b32 v54, v62, v53
	v_bfe_u32 v52, v50, 16, 1
	v_add3_u32 v52, v50, v52, s64
	v_bfe_u32 v50, v51, 16, 1
	v_lshrrev_b32_e32 v60, 16, v52
	s_waitcnt lgkmcnt(0)
	v_add_f32_e32 v52, v53, v54
	v_add3_u32 v51, v51, v50, s64
	v_lshrrev_b32_e32 v50, 16, v56
	v_fmamk_f32 v61, v52, 0x3a800000, v94
	s_waitcnt vmcnt(10)
	v_pk_mul_f32 v[52:53], v[32:33], v[32:33]
	v_pk_mul_f32 v[54:55], v[30:31], v[30:31]
	v_and_or_b32 v50, v57, s66, v50
	v_pk_mov_b32 v[56:57], v[54:55], v[52:53] op_sel:[1,0]
	v_mov_b32_e32 v55, v53
	v_pk_add_f32 v[52:53], v[56:57], v[54:55]
	s_waitcnt vmcnt(9)
	v_pk_mul_f32 v[54:55], v[28:29], v[28:29]
	v_pk_mul_f32 v[56:57], v[26:27], v[26:27]
	v_pk_add_f32 v[52:53], v[52:53], v[52:53] op_sel:[0,1] op_sel_hi:[1,0]
	v_pk_mov_b32 v[58:59], v[56:57], v[54:55] op_sel:[1,0]
	v_mov_b32_e32 v57, v55
	v_pk_add_f32 v[54:55], v[58:59], v[56:57]
	s_waitcnt vmcnt(7)
	v_mul_f32_e32 v53, v18, v18
	v_pk_add_f32 v[54:55], v[54:55], v[54:55] op_sel:[0,1] op_sel_hi:[1,0]
	v_mul_f32_e32 v56, v25, v25
	v_mul_f32_e32 v55, v19, v19
	v_pk_add_f32 v[52:53], v[52:53], v[54:55]
	v_mul_f32_e32 v54, v23, v23
	v_pk_fma_f32 v[54:55], v[22:23], v[22:23], v[54:55] op_sel_hi:[1,1,0]
	v_pk_fma_f32 v[56:57], v[24:25], v[24:25], v[56:57] op_sel_hi:[1,1,0]
	v_mul_f32_e32 v55, v20, v20
	v_mul_f32_e32 v57, v21, v21
	v_pk_add_f32 v[54:55], v[54:55], v[56:57]
	v_mul_f32_e32 v89, 0x4f800000, v61
	v_pk_add_f32 v[52:53], v[52:53], v[54:55]
	v_cmp_gt_f32_e32 vcc, s69, v61
	v_add_f32_e32 v52, v52, v53
	ds_bpermute_b32 v1, v1, v52
	v_cndmask_b32_e32 v53, v61, v89, vcc
	v_sqrt_f32_e32 v54, v53
	v_and_or_b32 v51, v51, s66, v60
	global_store_dwordx2 v[100:101], v[50:51], off offset:1536 sc1
	s_waitcnt lgkmcnt(0)
	v_add_f32_e32 v1, v52, v1
	ds_bpermute_b32 v52, v93, v1
	v_add_u32_e32 v55, -1, v54
	v_fma_f32 v56, -v55, v54, v53
	v_cmp_ge_f32_e64 s[4:5], 0, v56
	v_add_u32_e32 v56, 1, v54
	s_waitcnt lgkmcnt(0)
	v_add_f32_e32 v1, v1, v52
	ds_bpermute_b32 v52, v92, v1
	v_cndmask_b32_e64 v55, v54, v55, s[4:5]
	v_fma_f32 v54, -v56, v54, v53
	v_cmp_lt_f32_e64 s[4:5], 0, v54
	s_waitcnt lgkmcnt(0)
	v_add_f32_e32 v1, v1, v52
	ds_bpermute_b32 v52, v86, v1
	v_cndmask_b32_e64 v54, v55, v56, s[4:5]
	v_mul_f32_e32 v55, 0x37800000, v54
	v_cndmask_b32_e32 v54, v54, v55, vcc
	v_cmp_class_f32_e32 vcc, v53, v95
	s_waitcnt lgkmcnt(0)
	v_add_f32_e32 v1, v1, v52
	ds_bpermute_b32 v52, v82, v1
	v_cndmask_b32_e32 v53, v54, v53, vcc
	v_div_scale_f32 v54, s[4:5], v53, v53, 1.0
	v_rcp_f32_e32 v55, v54
	s_waitcnt lgkmcnt(0)
	v_add_f32_e32 v1, v1, v52
	ds_bpermute_b32 v50, v62, v1
	v_fma_f32 v51, -v54, v55, 1.0
	v_fmac_f32_e32 v55, v51, v55
	v_div_scale_f32 v51, vcc, 1.0, v53, 1.0
	s_waitcnt lgkmcnt(0)
	v_add_f32_e32 v1, v1, v50
	v_fmamk_f32 v1, v1, 0x3a800000, v94
	v_mul_f32_e32 v50, 0x4f800000, v1
	v_cmp_gt_f32_e64 s[4:5], s69, v1
	v_mul_f32_e32 v52, v51, v55
	v_fma_f32 v56, -v54, v52, v51
	v_cndmask_b32_e64 v1, v1, v50, s[4:5]
	v_sqrt_f32_e32 v50, v1
	v_fmac_f32_e32 v52, v56, v55
	v_fma_f32 v51, -v54, v52, v51
	v_div_fmas_f32 v51, v51, v55, v52
	v_add_u32_e32 v56, -1, v50
	v_fma_f32 v57, -v56, v50, v1
	v_cmp_ge_f32_e64 s[6:7], 0, v57
	v_add_u32_e32 v57, 1, v50
	s_nop 0
	v_cndmask_b32_e64 v56, v50, v56, s[6:7]
	v_fma_f32 v50, -v57, v50, v1
	v_cmp_lt_f32_e64 s[6:7], 0, v50
	s_nop 1
	v_cndmask_b32_e64 v50, v56, v57, s[6:7]
	v_mul_f32_e32 v56, 0x37800000, v50
	v_cndmask_b32_e64 v50, v50, v56, s[4:5]
	v_cmp_class_f32_e64 s[4:5], v1, v95
	s_nop 1
	v_cndmask_b32_e64 v1, v50, v1, s[4:5]
	v_div_scale_f32 v50, s[4:5], v1, v1, 1.0
	v_rcp_f32_e32 v56, v50
	s_lshl_b64 s[4:5], s[42:43], 11
	v_fma_f32 v52, -v50, v56, 1.0
	v_fmac_f32_e32 v56, v52, v56
	v_div_scale_f32 v52, vcc, 1.0, v1, 1.0
	v_mul_f32_e32 v54, v52, v56
	v_fma_f32 v55, -v50, v54, v52
	v_fmac_f32_e32 v54, v55, v56
	v_fma_f32 v50, -v50, v54, v52
	v_div_fmas_f32 v52, v50, v56, v54
	v_div_fixup_f32 v50, v51, v53, 1.0
	v_pk_mul_f32 v[46:47], v[46:47], v[50:51] op_sel_hi:[1,0]
	v_pk_mul_f32 v[48:49], v[48:49], v[50:51] op_sel_hi:[1,0]
	v_pk_mul_f32 v[46:47], v[2:3], v[46:47]
	s_nop 0
	v_bfe_u32 v51, v46, 16, 1
	v_add3_u32 v51, v46, v51, s64
	v_bfe_u32 v46, v47, 16, 1
	v_add3_u32 v53, v47, v46, s64
	v_pk_mul_f32 v[46:47], v[4:5], v[48:49]
	v_pk_mul_f32 v[42:43], v[42:43], v[50:51] op_sel_hi:[1,0]
	v_bfe_u32 v48, v46, 16, 1
	v_add3_u32 v49, v46, v48, s64
	v_bfe_u32 v46, v47, 16, 1
	v_add3_u32 v47, v47, v46, s64
	v_div_fixup_f32 v46, v52, v1, 1.0
	v_lshrrev_b32_e32 v1, 16, v51
	v_and_or_b32 v48, v53, s66, v1
	v_lshrrev_b32_e32 v1, 16, v49
	v_pk_mul_f32 v[42:43], v[6:7], v[42:43]
	v_and_or_b32 v49, v47, s66, v1
	v_bfe_u32 v1, v42, 16, 1
	v_pk_mul_f32 v[44:45], v[44:45], v[50:51] op_sel_hi:[1,0]
	v_add3_u32 v1, v42, v1, s64
	v_bfe_u32 v42, v43, 16, 1
	v_pk_mul_f32 v[44:45], v[8:9], v[44:45]
	v_lshrrev_b32_e32 v1, 16, v1
	v_add3_u32 v42, v43, v42, s64
	v_and_or_b32 v42, v42, s66, v1
	v_bfe_u32 v1, v44, 16, 1
	v_add3_u32 v1, v44, v1, s64
	v_bfe_u32 v43, v45, 16, 1
	v_pk_mul_f32 v[38:39], v[38:39], v[50:51] op_sel_hi:[1,0]
	v_lshrrev_b32_e32 v1, 16, v1
	v_add3_u32 v43, v45, v43, s64
	v_pk_mul_f32 v[38:39], v[10:11], v[38:39]
	v_and_or_b32 v43, v43, s66, v1
	v_bfe_u32 v1, v38, 16, 1
	v_pk_mul_f32 v[40:41], v[40:41], v[50:51] op_sel_hi:[1,0]
	v_add3_u32 v1, v38, v1, s64
	v_bfe_u32 v38, v39, 16, 1
	v_pk_mul_f32 v[40:41], v[12:13], v[40:41]
	v_lshrrev_b32_e32 v1, 16, v1
	v_add3_u32 v38, v39, v38, s64
	v_and_or_b32 v38, v38, s66, v1
	v_bfe_u32 v1, v40, 16, 1
	v_add3_u32 v1, v40, v1, s64
	v_bfe_u32 v39, v41, 16, 1
	v_pk_mul_f32 v[34:35], v[34:35], v[50:51] op_sel_hi:[1,0]
	v_lshrrev_b32_e32 v1, 16, v1
	v_add3_u32 v39, v41, v39, s64
	v_pk_mul_f32 v[34:35], v[14:15], v[34:35]
	v_and_or_b32 v39, v39, s66, v1
	v_bfe_u32 v1, v34, 16, 1
	v_pk_mul_f32 v[36:37], v[36:37], v[50:51] op_sel_hi:[1,0]
	v_add3_u32 v1, v34, v1, s64
	v_bfe_u32 v34, v35, 16, 1
	v_pk_mul_f32 v[36:37], v[16:17], v[36:37]
	v_lshrrev_b32_e32 v1, 16, v1
	v_add3_u32 v34, v35, v34, s64
	v_and_or_b32 v34, v34, s66, v1
	v_bfe_u32 v1, v36, 16, 1
	v_add3_u32 v1, v36, v1, s64
	v_bfe_u32 v35, v37, 16, 1
	v_pk_mul_f32 v[30:31], v[30:31], v[46:47] op_sel_hi:[1,0]
	v_lshrrev_b32_e32 v1, 16, v1
	v_add3_u32 v35, v37, v35, s64
	v_pk_mul_f32 v[30:31], v[2:3], v[30:31]
	v_and_or_b32 v35, v35, s66, v1
	v_bfe_u32 v1, v30, 16, 1
	v_pk_mul_f32 v[32:33], v[32:33], v[46:47] op_sel_hi:[1,0]
	v_add3_u32 v1, v30, v1, s64
	v_bfe_u32 v30, v31, 16, 1
	v_pk_mul_f32 v[32:33], v[4:5], v[32:33]
	v_lshrrev_b32_e32 v1, 16, v1
	v_add3_u32 v30, v31, v30, s64
	v_and_or_b32 v30, v30, s66, v1
	v_bfe_u32 v1, v32, 16, 1
	v_add3_u32 v1, v32, v1, s64
	v_bfe_u32 v31, v33, 16, 1
	v_pk_mul_f32 v[26:27], v[26:27], v[46:47] op_sel_hi:[1,0]
	v_lshrrev_b32_e32 v1, 16, v1
	v_add3_u32 v31, v33, v31, s64
	v_pk_mul_f32 v[26:27], v[6:7], v[26:27]
	v_and_or_b32 v31, v31, s66, v1
	v_bfe_u32 v1, v26, 16, 1
	v_pk_mul_f32 v[28:29], v[28:29], v[46:47] op_sel_hi:[1,0]
	v_add3_u32 v1, v26, v1, s64
	v_bfe_u32 v26, v27, 16, 1
	v_pk_mul_f32 v[28:29], v[8:9], v[28:29]
	v_lshrrev_b32_e32 v1, 16, v1
	v_add3_u32 v26, v27, v26, s64
	v_and_or_b32 v26, v26, s66, v1
	v_bfe_u32 v1, v28, 16, 1
	v_add3_u32 v1, v28, v1, s64
	v_bfe_u32 v27, v29, 16, 1
	v_pk_mul_f32 v[22:23], v[22:23], v[46:47] op_sel_hi:[1,0]
	v_lshrrev_b32_e32 v1, 16, v1
	v_add3_u32 v27, v29, v27, s64
	v_pk_mul_f32 v[22:23], v[10:11], v[22:23]
	v_and_or_b32 v27, v27, s66, v1
	v_bfe_u32 v1, v22, 16, 1
	v_pk_mul_f32 v[24:25], v[24:25], v[46:47] op_sel_hi:[1,0]
	v_add3_u32 v1, v22, v1, s64
	v_bfe_u32 v22, v23, 16, 1
	v_pk_mul_f32 v[24:25], v[12:13], v[24:25]
	v_lshrrev_b32_e32 v1, 16, v1
	v_add3_u32 v22, v23, v22, s64
	v_and_or_b32 v22, v22, s66, v1
	v_bfe_u32 v1, v24, 16, 1
	v_add3_u32 v1, v24, v1, s64
	v_bfe_u32 v23, v25, 16, 1
	v_pk_mul_f32 v[18:19], v[18:19], v[46:47] op_sel_hi:[1,0]
	v_lshrrev_b32_e32 v1, 16, v1
	v_add3_u32 v23, v25, v23, s64
	v_pk_mul_f32 v[18:19], v[14:15], v[18:19]
	v_and_or_b32 v23, v23, s66, v1
	v_bfe_u32 v1, v18, 16, 1
	v_pk_mul_f32 v[20:21], v[20:21], v[46:47] op_sel_hi:[1,0]
	v_add3_u32 v1, v18, v1, s64
	v_bfe_u32 v18, v19, 16, 1
	v_pk_mul_f32 v[20:21], v[16:17], v[20:21]
	v_lshrrev_b32_e32 v1, 16, v1
	v_add3_u32 v18, v19, v18, s64
	v_and_or_b32 v18, v18, s66, v1
	v_bfe_u32 v1, v20, 16, 1
	v_add3_u32 v1, v20, v1, s64
	v_bfe_u32 v19, v21, 16, 1
	v_lshl_add_u64 v[52:53], v[90:91], 0, s[4:5]
	s_lshl_b64 s[4:5], s[10:11], 11
	v_lshrrev_b32_e32 v1, 16, v1
	v_add3_u32 v19, v21, v19, s64
	global_store_dwordx2 v[52:53], v[48:49], off sc1
	global_store_dwordx2 v[52:53], v[42:43], off offset:512 sc1
	global_store_dwordx2 v[52:53], v[38:39], off offset:1024 sc1
	global_store_dwordx2 v[52:53], v[34:35], off offset:1536 sc1
	v_lshl_add_u64 v[34:35], v[90:91], 0, s[4:5]
	v_and_or_b32 v19, v19, s66, v1
	v_readfirstlane_b32 s10, v150
	global_store_dwordx2 v[34:35], v[30:31], off sc1
	global_store_dwordx2 v[34:35], v[26:27], off offset:512 sc1
	global_store_dwordx2 v[34:35], v[22:23], off offset:1024 sc1
	global_store_dwordx2 v[34:35], v[18:19], off offset:1536 sc1

.LBB0_415:
	s_or_b64 exec, exec, s[26:27]
	v_readfirstlane_b32 s28, v70

.LBB0_417:
	v_mov_b32_e32 v46, v184
	v_mov_b32_e32 v1, 0
	v_cmp_eq_u32_e32 vcc, 0, v46
	s_and_saveexec_b64 s[26:27], vcc
	s_cbranch_execz .LBB0_421
	s_mov_b64 s[30:31], exec
	v_mbcnt_lo_u32_b32 v1, s30, 0
	v_mbcnt_hi_u32_b32 v1, s31, v1
	v_cmp_eq_u32_e32 vcc, 0, v1
	s_and_saveexec_b64 s[28:29], vcc
	s_cbranch_execz .LBB0_420
	s_bcnt1_i32_b64 s30, s[30:31]
	v_mov_b32_e32 v2, s30
	global_atomic_add v70, v35, v2, s[4:5] sc0
.LBB0_420:
	s_or_b64 exec, exec, s[28:29]
.LBB0_421:
	s_or_b64 exec, exec, s[26:27]
	v_lshlrev_b32_e32 v2, 8, v46
	v_lshlrev_b32_e32 v3, 3, v46
	s_mov_b64 s[26:27], -1
	s_cmpk_gt_i32 s38, 0x1fff
	v_and_b32_e32 v38, 0xe00, v2
	v_and_b32_e32 v34, 8, v3
	v_and_b32_e32 v40, 0x800, v2
	v_and_b32_e32 v36, 56, v3
	s_cbranch_scc0 .LBB0_431
	s_load_dwordx4 s[28:31], s[20:21], 0x10
	s_add_i32 s26, s38, 0xffffe000
	v_lshlrev_b32_e32 v2, 2, v46
	v_lshl_add_u32 v2, s26, 10, v2
	v_ashrrev_i32_e32 v3, 31, v2
	v_lshlrev_b64 v[2:3], 2, v[2:3]
	s_waitcnt lgkmcnt(0)
	v_lshl_add_u64 v[42:43], s[28:29], 0, v[2:3]
	v_lshl_add_u64 v[44:45], s[30:31], 0, v[2:3]
	global_load_dwordx4 v[26:29], v[42:43], off
	global_load_dwordx4 v[22:25], v[42:43], off offset:1024
	global_load_dwordx4 v[30:33], v[44:45], off
	global_load_dwordx4 v[18:21], v[44:45], off offset:1024
	global_load_dwordx4 v[10:13], v[42:43], off offset:2048
	global_load_dwordx4 v[6:9], v[42:43], off offset:3072
	global_load_dwordx4 v[14:17], v[44:45], off offset:2048
	global_load_dwordx4 v[2:5], v[44:45], off offset:3072
	v_mov_b32_e32 v41, v35
	v_lshl_add_u32 v47, s26, 8, v46
	v_mov_b32_e32 v39, v35
	v_lshl_add_u64 v[42:43], s[8:9], 0, v[40:41]
	v_lshlrev_b32_e32 v41, 2, v47
	v_lshl_add_u64 v[44:45], s[6:7], 0, v[38:39]
	v_ashrrev_i32_e32 v39, 12, v47
	v_lshrrev_b32_e32 v49, 5, v47
	v_bfe_u32 v54, v41, 6, 1
	v_bfe_u32 v49, v49, 5, 2
	v_lshl_or_b32 v54, v39, 1, v54
	v_mad_i32_i24 v54, v54, 5, v49
	v_ashrrev_i32_e32 v55, 31, v54
	v_bfe_u32 v52, v47, 5, 5
	v_lshlrev_b64 v[54:55], 12, v[54:55]
	v_mov_b32_e32 v51, v35
	v_mov_b32_e32 v53, v35
	v_lshlrev_b32_e32 v50, 4, v52
	v_lshlrev_b32_e32 v52, 6, v52
	v_lshl_add_u64 v[56:57], v[44:45], 0, v[54:55]
	v_lshl_add_u64 v[54:55], v[42:43], 0, v[54:55]
	v_lshl_add_u64 v[50:51], v[56:57], 0, v[50:51]
	v_lshl_add_u64 v[52:53], v[54:55], 0, v[52:53]
	v_bfe_u32 v48, v47, 5, 7
	v_mov_b32_e32 v37, v35
	v_lshl_add_u64 v[50:51], v[50:51], 0, v[34:35]
	v_cmp_lt_u32_e32 vcc, 31, v48
	v_lshl_add_u64 v[52:53], v[52:53], 0, v[36:37]
	s_waitcnt vmcnt(0)
	v_mov_b32_e32 v54, v26
	v_mov_b32_e32 v55, v22
	v_mov_b32_e32 v56, v30
	v_mov_b32_e32 v57, v18
	v_mov_b32_e32 v58, v10
	v_mov_b32_e32 v59, v6
	v_mov_b32_e32 v60, v14
	v_mov_b32_e32 v61, v2
	v_bfe_u32 v49, v26, 16, 1
	v_bfe_u32 v63, v28, 16, 1
	v_pk_add_f32 v[54:55], v[54:55], v[56:57]
	v_bfe_u32 v62, v27, 16, 1
	v_bfe_u32 v64, v29, 16, 1
	v_bfe_u32 v65, v30, 16, 1
	v_bfe_u32 v67, v32, 16, 1
	v_pk_add_f32 v[56:57], v[58:59], v[60:61]
	v_add3_u32 v49, v26, v49, s36
	v_add3_u32 v59, v28, v63, s36
	v_add_f32_e32 v54, 0, v54
	v_bfe_u32 v66, v31, 16, 1
	v_bfe_u32 v68, v33, 16, 1
	v_add3_u32 v58, v27, v62, s36
	v_add3_u32 v60, v29, v64, s36
	v_add3_u32 v61, v30, v65, s36
	v_add3_u32 v63, v32, v67, s36
	v_lshrrev_b32_e32 v49, 16, v49
	v_lshrrev_b32_e32 v59, 16, v59
	v_add_f32_e32 v65, v54, v55
	v_add3_u32 v62, v31, v66, s36
	v_add3_u32 v64, v33, v68, s36
	v_lshrrev_b32_e32 v61, 16, v61
	v_lshrrev_b32_e32 v63, 16, v63
	v_and_or_b32 v54, v58, s37, v49
	v_and_or_b32 v55, v60, s37, v59
	v_add_f32_e32 v49, v65, v56
	v_and_or_b32 v58, v62, s37, v61
	v_and_or_b32 v59, v64, s37, v63
	v_add_f32_e32 v49, v49, v57
	global_store_dwordx2 v[50:51], v[54:55], off sc1
	global_store_dwordx2 v[52:53], v[58:59], off sc1
	s_and_saveexec_b64 s[26:27], vcc
	s_cbranch_execz .LBB0_424
	v_lshl_or_b32 v39, v39, 7, v48
	v_subrev_u32_e32 v48, 32, v39
	v_ashrrev_i32_e32 v49, 31, v48
	v_and_b32_e32 v41, 0x7c, v41
	v_lshlrev_b64 v[48:49], 9, v[48:49]
	v_lshl_or_b32 v48, v41, 2, v48
	v_lshl_add_u64 v[50:51], s[10:11], 0, v[48:49]
	global_store_dwordx4 v[50:51], v[26:29], off sc0 sc1
	s_nop 1
	v_lshl_add_u64 v[26:27], s[12:13], 0, v[48:49]
	global_store_dwordx4 v[26:27], v[30:33], off sc0 sc1
	s_nop 1

.LBB0_430:
	s_or_b64 exec, exec, s[26:27]
	v_readfirstlane_b32 s28, v70
	s_mov_b64 s[26:27], 0

.LBB0_501:
	v_mov_b32_e32 v186, v184
	v_mov_b32_e32 v187, 0
	s_and_saveexec_b64 s[6:7], s[4:5]
	s_cbranch_execz .LBB0_505
	s_mov_b64 s[14:15], exec
	v_mbcnt_lo_u32_b32 v2, s14, 0
	v_mbcnt_hi_u32_b32 v2, s15, v2
	v_cmp_eq_u32_e32 vcc, 0, v2
	s_and_saveexec_b64 s[8:9], vcc
	s_cbranch_execz .LBB0_504
	s_bcnt1_i32_b64 s13, s[14:15]
	v_mov_b32_e32 v4, s13
	global_atomic_add v252, v3, v4, s[16:17] offset:2048 sc0
.LBB0_504:
	s_or_b64 exec, exec, s[8:9]
.LBB0_505:
	s_or_b64 exec, exec, s[6:7]
	s_cmpk_gt_i32 s25, 0xfff
	s_mov_b64 s[6:7], -1
	s_cbranch_scc0 .LBB0_514
	s_cmpk_gt_u32 s25, 0x10ff
	s_mov_b64 s[8:9], -1
	s_cbranch_scc0 .LBB0_512
	s_mov_b64 s[14:15], -1
	s_cmpk_gt_u32 s25, 0x20ff
	s_cbranch_scc0 .LBB0_509
	s_add_i32 s6, s25, 0xffffdf00
	s_lshr_b32 s37, s6, 3
	s_mov_b64 s[6:7], 0

.LBB0_551:
	s_mov_b32 s37, 3
	s_movk_i32 s38, 0x2000
	s_add_i32 s39, s37, -1
	s_cmp_ge_i32 s39, s73
	s_mov_b64 s[14:15], -1
	s_cbranch_scc0 .LBB0_554
	s_branch .LBB0_553

.LBB0_558:
	v_xor_b32_e32 v116, 0x80000000, v192
	v_mov_b32_e32 v117, v116
	v_mov_b32_e32 v118, v116
	v_mov_b32_e32 v119, v116
	v_mov_b32_e32 v120, v116
	v_mov_b32_e32 v121, v116
	v_mov_b32_e32 v122, v116
	v_mov_b32_e32 v123, v116
	v_mov_b32_e32 v124, v116
	v_mov_b32_e32 v125, v116
	v_mov_b32_e32 v126, v116
	v_mov_b32_e32 v127, v116
	v_mov_b32_e32 v128, v116
	v_mov_b32_e32 v129, v116
	v_mov_b32_e32 v130, v116
	v_mov_b32_e32 v131, v116
	s_add_i32 s13, s78, s69
	s_lshl_b32 s41, s13, 5
	s_waitcnt lgkmcnt(11)
	v_mfma_f32_32x32x16_bf16 v[116:131], v[180:183], v[148:151], v[116:131]
	s_add_i32 s41, s41, s72
	s_cmp_gt_i32 s41, s76
	s_cselect_b64 s[14:15], -1, 0
	v_add_u32_e32 v194, s41, v190
	s_and_b64 s[14:15], s[8:9], s[14:15]
	v_sub_u32_e32 v194, v193, v194
	s_andn2_b64 vcc, exec, s[14:15]
	s_waitcnt lgkmcnt(10)
	v_mfma_f32_32x32x16_bf16 v[116:131], v[176:179], v[144:147], v[116:131]
	s_waitcnt lgkmcnt(9)
	v_mfma_f32_32x32x16_bf16 v[116:131], v[172:175], v[132:135], v[116:131]
	s_waitcnt lgkmcnt(8)
	v_mfma_f32_32x32x16_bf16 v[116:131], v[168:171], v[12:15], v[116:131]
	s_cbranch_vccnz .LBB0_560
	v_add_u32_e32 v195, 0x80, v194
	v_med3_i32 v196, v195, 0, v185
	v_lshl_add_u32 v204, v196, 2, s75
	v_max_i32_e32 v196, 1, v195
	v_add_u32_e32 v196, -1, v196
	v_min_u32_e32 v196, 0x100, v196
	v_lshl_add_u32 v205, v196, 2, s75
	v_max_i32_e32 v196, 2, v195
	v_add_u32_e32 v196, -2, v196
	v_min_u32_e32 v196, 0x100, v196
	v_lshl_add_u32 v206, v196, 2, s75
	v_max_i32_e32 v196, 3, v195
	v_add_u32_e32 v196, -3, v196
	v_min_u32_e32 v196, 0x100, v196
	v_lshl_add_u32 v207, v196, 2, s75
	v_max_i32_e32 v196, 8, v195
	v_add_u32_e32 v196, -8, v196
	v_min_u32_e32 v196, 0x100, v196
	v_lshl_add_u32 v208, v196, 2, s75
	v_max_i32_e32 v196, 9, v195
	v_add_u32_e32 v196, -9, v196
	v_min_u32_e32 v196, 0x100, v196
	v_lshl_add_u32 v209, v196, 2, s75
	v_max_i32_e32 v196, 10, v195
	v_add_u32_e32 v196, -10, v196
	v_min_u32_e32 v196, 0x100, v196
	v_lshl_add_u32 v210, v196, 2, s75
	v_max_i32_e32 v196, 11, v195
	v_add_u32_e32 v196, -11, v196
	v_min_u32_e32 v196, 0x100, v196
	v_lshl_add_u32 v211, v196, 2, s75
	v_max_i32_e32 v196, 16, v195
	v_max_i32_e32 v197, 17, v195
	v_max_i32_e32 v198, 18, v195
	v_max_i32_e32 v199, 19, v195
	v_max_i32_e32 v200, 24, v195
	v_max_i32_e32 v201, 25, v195
	v_max_i32_e32 v202, 26, v195
	v_add_u32_e32 v196, -16, v196
	v_subrev_u32_e32 v197, 17, v197
	v_subrev_u32_e32 v198, 18, v198
	v_subrev_u32_e32 v199, 19, v199
	v_subrev_u32_e32 v200, 24, v200
	v_subrev_u32_e32 v201, 25, v201
	v_subrev_u32_e32 v202, 26, v202
	v_max_i32_e32 v195, 27, v195
	v_min_u32_e32 v196, 0x100, v196
	v_min_u32_e32 v197, 0x100, v197
	v_min_u32_e32 v198, 0x100, v198
	v_min_u32_e32 v199, 0x100, v199
	v_min_u32_e32 v200, 0x100, v200
	v_min_u32_e32 v201, 0x100, v201
	v_min_u32_e32 v202, 0x100, v202
	v_subrev_u32_e32 v195, 27, v195
	v_lshl_add_u32 v196, v196, 2, s75
	v_lshl_add_u32 v197, v197, 2, s75
	v_lshl_add_u32 v198, v198, 2, s75
	v_lshl_add_u32 v199, v199, 2, s75
	v_lshl_add_u32 v200, v200, 2, s75
	v_lshl_add_u32 v201, v201, 2, s75
	v_lshl_add_u32 v202, v202, 2, s75
	v_min_u32_e32 v195, 0x100, v195
	v_lshl_add_u32 v195, v195, 2, s75
	ds_read_b32 v196, v196
	ds_read_b32 v197, v197
	ds_read_b32 v198, v198
	ds_read_b32 v199, v199
	ds_read_b32 v200, v200
	ds_read_b32 v201, v201
	ds_read_b32 v202, v202
	ds_read_b32 v203, v195
	ds_read_b32 v204, v204
	ds_read_b32 v205, v205
	ds_read_b32 v206, v206
	ds_read_b32 v207, v207
	ds_read_b32 v208, v208
	ds_read_b32 v209, v209
	ds_read_b32 v210, v210
	ds_read_b32 v211, v211
	s_waitcnt lgkmcnt(8)
	v_pk_add_f32 v[130:131], v[130:131], v[202:203]
	v_pk_add_f32 v[128:129], v[128:129], v[200:201]
	v_pk_add_f32 v[126:127], v[126:127], v[198:199]
	v_pk_add_f32 v[124:125], v[124:125], v[196:197]
	s_waitcnt lgkmcnt(0)
	v_pk_add_f32 v[122:123], v[122:123], v[210:211]
	v_pk_add_f32 v[120:121], v[120:121], v[208:209]
	v_pk_add_f32 v[118:119], v[118:119], v[206:207]
	v_pk_add_f32 v[116:117], v[116:117], v[204:205]
.LBB0_560:
	s_nop 0
	v_max3_f32 v195, v116, v117, v118
	v_max3_f32 v196, v119, v120, v121
	s_nop 0
	v_max3_f32 v195, v195, v122, v123
	v_max3_f32 v196, v196, v124, v125
	s_nop 0
	v_max3_f32 v195, v195, v126, v127
	v_max3_f32 v196, v196, v128, v129
	s_nop 0
	v_max3_f32 v195, v195, v130, v131
	v_max_f32_e32 v196, v196, v196
	v_max_f32_e32 v195, v195, v195
	v_max_f32_e32 v195, v195, v196
	v_mov_b32_e32 v196, v195
	s_nop 1
	v_permlane32_swap_b32_e32 v195, v196
	v_max_f32_e32 v196, v196, v196
	v_max_f32_e32 v195, v195, v195
	v_max_f32_e32 v195, v195, v196
	v_cmp_lt_f32_e32 vcc, s66, v195
	s_cbranch_vccz .LBB0_562
	v_max_f32_e32 v195, v195, v195
	v_max_f32_e32 v196, 0, v195
	v_exp_f32_e64 v198, -v196
	v_add_f32_e32 v192, v192, v196
	v_pk_add_f32 v[116:117], v[116:117], v[196:197] op_sel_hi:[1,0] neg_lo:[0,1] neg_hi:[0,1]
	v_pk_add_f32 v[118:119], v[118:119], v[196:197] op_sel_hi:[1,0] neg_lo:[0,1] neg_hi:[0,1]
	v_pk_add_f32 v[120:121], v[120:121], v[196:197] op_sel_hi:[1,0] neg_lo:[0,1] neg_hi:[0,1]
	v_pk_add_f32 v[122:123], v[122:123], v[196:197] op_sel_hi:[1,0] neg_lo:[0,1] neg_hi:[0,1]
	v_pk_add_f32 v[124:125], v[124:125], v[196:197] op_sel_hi:[1,0] neg_lo:[0,1] neg_hi:[0,1]
	v_pk_add_f32 v[126:127], v[126:127], v[196:197] op_sel_hi:[1,0] neg_lo:[0,1] neg_hi:[0,1]
	v_pk_add_f32 v[128:129], v[128:129], v[196:197] op_sel_hi:[1,0] neg_lo:[0,1] neg_hi:[0,1]
	v_pk_add_f32 v[130:131], v[130:131], v[196:197] op_sel_hi:[1,0] neg_lo:[0,1] neg_hi:[0,1]
	v_pk_mul_f32 v[66:67], v[66:67], v[198:199] op_sel_hi:[1,0]
	v_pk_mul_f32 v[64:65], v[64:65], v[198:199] op_sel_hi:[1,0]
	v_pk_mul_f32 v[62:63], v[62:63], v[198:199] op_sel_hi:[1,0]
	v_pk_mul_f32 v[60:61], v[60:61], v[198:199] op_sel_hi:[1,0]
	v_pk_mul_f32 v[58:59], v[58:59], v[198:199] op_sel_hi:[1,0]
	v_pk_mul_f32 v[56:57], v[56:57], v[198:199] op_sel_hi:[1,0]
	v_pk_mul_f32 v[54:55], v[54:55], v[198:199] op_sel_hi:[1,0]
	v_pk_mul_f32 v[52:53], v[52:53], v[198:199] op_sel_hi:[1,0]
	v_pk_mul_f32 v[82:83], v[82:83], v[198:199] op_sel_hi:[1,0]
	v_pk_mul_f32 v[80:81], v[80:81], v[198:199] op_sel_hi:[1,0]
	v_pk_mul_f32 v[78:79], v[78:79], v[198:199] op_sel_hi:[1,0]
	v_pk_mul_f32 v[76:77], v[76:77], v[198:199] op_sel_hi:[1,0]
	v_pk_mul_f32 v[74:75], v[74:75], v[198:199] op_sel_hi:[1,0]
	v_pk_mul_f32 v[72:73], v[72:73], v[198:199] op_sel_hi:[1,0]
	v_pk_mul_f32 v[70:71], v[70:71], v[198:199] op_sel_hi:[1,0]
	v_pk_mul_f32 v[68:69], v[68:69], v[198:199] op_sel_hi:[1,0]
	v_pk_mul_f32 v[114:115], v[114:115], v[198:199] op_sel_hi:[1,0]
	v_pk_mul_f32 v[112:113], v[112:113], v[198:199] op_sel_hi:[1,0]
	v_pk_mul_f32 v[110:111], v[110:111], v[198:199] op_sel_hi:[1,0]
	v_pk_mul_f32 v[108:109], v[108:109], v[198:199] op_sel_hi:[1,0]
	v_pk_mul_f32 v[106:107], v[106:107], v[198:199] op_sel_hi:[1,0]
	v_pk_mul_f32 v[104:105], v[104:105], v[198:199] op_sel_hi:[1,0]
	v_pk_mul_f32 v[102:103], v[102:103], v[198:199] op_sel_hi:[1,0]
	v_pk_mul_f32 v[100:101], v[100:101], v[198:199] op_sel_hi:[1,0]
.LBB0_562:
	s_mov_b32 s14, s12
	s_mov_b32 s15, s12
	v_exp_f32_e32 v195, v116
	v_exp_f32_e32 v196, v117
	v_exp_f32_e32 v197, v118
	v_exp_f32_e32 v198, v119
	s_mov_b32 s13, s12
	v_mov_b64_e32 v[118:119], s[14:15]
	v_exp_f32_e32 v199, v120
	v_exp_f32_e32 v200, v121
	v_exp_f32_e32 v201, v122
	v_exp_f32_e32 v123, v123
	v_mov_b64_e32 v[116:117], s[12:13]
	v_cvt_pk_bf16_f32 v120, v195, v196
	v_cvt_pk_bf16_f32 v121, v197, v198
	v_cvt_pk_bf16_f32 v122, v199, v200
	v_cvt_pk_bf16_f32 v123, v201, v123
	v_exp_f32_e32 v124, v124
	v_exp_f32_e32 v125, v125
	v_mfma_f32_32x32x16_bf16 v[100:115], v[116:119], v[120:123], v[100:115]
	v_exp_f32_e32 v126, v126
	v_exp_f32_e32 v127, v127
	v_exp_f32_e32 v128, v128
	v_exp_f32_e32 v129, v129
	v_exp_f32_e32 v130, v130
	v_exp_f32_e32 v131, v131
	v_cvt_pk_bf16_f32 v124, v124, v125
	s_waitcnt lgkmcnt(6)
	v_mfma_f32_32x32x16_bf16 v[52:67], v[152:155], v[120:123], v[52:67]
	v_cvt_pk_bf16_f32 v125, v126, v127
	v_cvt_pk_bf16_f32 v126, v128, v129
	v_cvt_pk_bf16_f32 v127, v130, v131
	s_and_b64 vcc, exec, s[6:7]
	s_waitcnt lgkmcnt(2)
	v_mfma_f32_32x32x16_bf16 v[68:83], v[160:163], v[120:123], v[68:83]
	v_mfma_f32_32x32x16_bf16 v[100:115], v[116:119], v[124:127], v[100:115]
	v_mfma_f32_32x32x16_bf16 v[52:67], v[156:159], v[124:127], v[52:67]
	s_waitcnt lgkmcnt(0)
	v_mfma_f32_32x32x16_bf16 v[68:83], v[164:167], v[124:127], v[68:83]
	s_cbranch_vccnz .LBB0_568
	v_xor_b32_e32 v116, 0x80000000, v19
	v_mov_b32_e32 v117, v116
	v_mov_b32_e32 v118, v116
	v_mov_b32_e32 v119, v116
	v_mov_b32_e32 v120, v116
	v_mov_b32_e32 v121, v116
	v_mov_b32_e32 v122, v116
	v_mov_b32_e32 v123, v116
	v_mov_b32_e32 v124, v116
	v_mov_b32_e32 v125, v116
	v_mov_b32_e32 v126, v116
	v_mov_b32_e32 v127, v116
	v_mov_b32_e32 v128, v116
	v_mov_b32_e32 v129, v116
	v_mov_b32_e32 v130, v116
	v_mov_b32_e32 v131, v116
	s_sub_i32 s13, s77, s41
	s_cmpk_lt_i32 s13, 0x9f
	v_mfma_f32_32x32x16_bf16 v[116:131], v[180:183], v[140:143], v[116:131]
	s_cselect_b64 s[14:15], -1, 0
	s_and_b64 s[14:15], s[8:9], s[14:15]
	s_andn2_b64 vcc, exec, s[14:15]
	v_mfma_f32_32x32x16_bf16 v[116:131], v[176:179], v[136:139], v[116:131]
	v_mfma_f32_32x32x16_bf16 v[116:131], v[172:175], v[8:11], v[116:131]
	v_mfma_f32_32x32x16_bf16 v[116:131], v[168:171], v[4:7], v[116:131]
	s_cbranch_vccnz .LBB0_565
	v_add_u32_e32 v168, 0xa0, v194
	v_med3_i32 v169, v168, 0, v185
	v_lshl_add_u32 v176, v169, 2, s75
	v_max_i32_e32 v169, 1, v168
	v_add_u32_e32 v169, -1, v169
	v_min_u32_e32 v169, 0x100, v169
	v_lshl_add_u32 v177, v169, 2, s75
	v_max_i32_e32 v169, 2, v168
	v_add_u32_e32 v169, -2, v169
	v_min_u32_e32 v169, 0x100, v169
	v_lshl_add_u32 v178, v169, 2, s75
	v_max_i32_e32 v169, 3, v168
	v_add_u32_e32 v169, -3, v169
	v_min_u32_e32 v169, 0x100, v169
	v_lshl_add_u32 v179, v169, 2, s75
	v_max_i32_e32 v169, 8, v168
	v_add_u32_e32 v169, -8, v169
	v_min_u32_e32 v169, 0x100, v169
	v_lshl_add_u32 v180, v169, 2, s75
	v_max_i32_e32 v169, 9, v168
	v_add_u32_e32 v169, -9, v169
	v_min_u32_e32 v169, 0x100, v169
	v_lshl_add_u32 v181, v169, 2, s75
	v_max_i32_e32 v169, 10, v168
	v_add_u32_e32 v169, -10, v169
	v_min_u32_e32 v169, 0x100, v169
	v_lshl_add_u32 v182, v169, 2, s75
	v_max_i32_e32 v169, 11, v168
	v_add_u32_e32 v169, -11, v169
	v_min_u32_e32 v169, 0x100, v169
	v_lshl_add_u32 v183, v169, 2, s75
	v_max_i32_e32 v169, 16, v168
	v_max_i32_e32 v170, 17, v168
	v_max_i32_e32 v171, 18, v168
	v_max_i32_e32 v172, 19, v168
	v_max_i32_e32 v173, 24, v168
	v_max_i32_e32 v174, 25, v168
	v_max_i32_e32 v175, 26, v168
	v_add_u32_e32 v169, -16, v169
	v_subrev_u32_e32 v170, 17, v170
	v_subrev_u32_e32 v171, 18, v171
	v_subrev_u32_e32 v172, 19, v172
	v_subrev_u32_e32 v173, 24, v173
	v_subrev_u32_e32 v174, 25, v174
	v_subrev_u32_e32 v175, 26, v175
	v_max_i32_e32 v168, 27, v168
	v_min_u32_e32 v169, 0x100, v169
	v_min_u32_e32 v170, 0x100, v170
	v_min_u32_e32 v171, 0x100, v171
	v_min_u32_e32 v172, 0x100, v172
	v_min_u32_e32 v173, 0x100, v173
	v_min_u32_e32 v174, 0x100, v174
	v_min_u32_e32 v175, 0x100, v175
	v_subrev_u32_e32 v168, 27, v168
	v_lshl_add_u32 v169, v169, 2, s75
	v_lshl_add_u32 v170, v170, 2, s75
	v_lshl_add_u32 v171, v171, 2, s75
	v_lshl_add_u32 v172, v172, 2, s75
	v_lshl_add_u32 v173, v173, 2, s75
	v_lshl_add_u32 v174, v174, 2, s75
	v_lshl_add_u32 v175, v175, 2, s75
	v_min_u32_e32 v168, 0x100, v168
	v_lshl_add_u32 v194, v168, 2, s75
	ds_read_b32 v168, v169
	ds_read_b32 v169, v170
	ds_read_b32 v170, v171
	ds_read_b32 v171, v172
	ds_read_b32 v172, v173
	ds_read_b32 v173, v174
	ds_read_b32 v174, v175
	ds_read_b32 v175, v194
	ds_read_b32 v176, v176
	ds_read_b32 v177, v177
	ds_read_b32 v178, v178
	ds_read_b32 v179, v179
	ds_read_b32 v180, v180
	ds_read_b32 v181, v181
	ds_read_b32 v182, v182
	ds_read_b32 v183, v183
	s_waitcnt lgkmcnt(8)
	v_pk_add_f32 v[130:131], v[130:131], v[174:175]
	v_pk_add_f32 v[128:129], v[128:129], v[172:173]
	v_pk_add_f32 v[126:127], v[126:127], v[170:171]
	v_pk_add_f32 v[124:125], v[124:125], v[168:169]
	s_waitcnt lgkmcnt(0)
	v_pk_add_f32 v[122:123], v[122:123], v[182:183]
	v_pk_add_f32 v[120:121], v[120:121], v[180:181]
	v_pk_add_f32 v[118:119], v[118:119], v[178:179]
	v_pk_add_f32 v[116:117], v[116:117], v[176:177]
.LBB0_565:
	s_nop 0
	v_max3_f32 v168, v116, v117, v118
	v_max3_f32 v169, v119, v120, v121
	s_nop 0
	v_max3_f32 v168, v168, v122, v123
	v_max3_f32 v169, v169, v124, v125
	s_nop 0
	v_max3_f32 v168, v168, v126, v127
	v_max3_f32 v169, v169, v128, v129
	s_nop 0
	v_max3_f32 v168, v168, v130, v131
	v_max_f32_e32 v169, v169, v169
	v_max_f32_e32 v168, v168, v168
	v_max_f32_e32 v168, v168, v169
	v_mov_b32_e32 v169, v168
	s_nop 1
	v_permlane32_swap_b32_e32 v168, v169
	v_max_f32_e32 v169, v169, v169
	v_max_f32_e32 v168, v168, v168
	v_max_f32_e32 v168, v168, v169
	v_cmp_lt_f32_e32 vcc, s66, v168
	s_cbranch_vccz .LBB0_567
	v_max_f32_e32 v168, v168, v168
	v_max_f32_e32 v168, 0, v168
	v_exp_f32_e64 v170, -v168
	v_add_f32_e32 v19, v19, v168
	v_pk_add_f32 v[116:117], v[116:117], v[168:169] op_sel_hi:[1,0] neg_lo:[0,1] neg_hi:[0,1]
	v_pk_add_f32 v[118:119], v[118:119], v[168:169] op_sel_hi:[1,0] neg_lo:[0,1] neg_hi:[0,1]
	v_pk_add_f32 v[120:121], v[120:121], v[168:169] op_sel_hi:[1,0] neg_lo:[0,1] neg_hi:[0,1]
	v_pk_add_f32 v[122:123], v[122:123], v[168:169] op_sel_hi:[1,0] neg_lo:[0,1] neg_hi:[0,1]
	v_pk_add_f32 v[124:125], v[124:125], v[168:169] op_sel_hi:[1,0] neg_lo:[0,1] neg_hi:[0,1]
	v_pk_add_f32 v[126:127], v[126:127], v[168:169] op_sel_hi:[1,0] neg_lo:[0,1] neg_hi:[0,1]
	v_pk_add_f32 v[128:129], v[128:129], v[168:169] op_sel_hi:[1,0] neg_lo:[0,1] neg_hi:[0,1]
	v_pk_add_f32 v[130:131], v[130:131], v[168:169] op_sel_hi:[1,0] neg_lo:[0,1] neg_hi:[0,1]
	v_pk_mul_f32 v[50:51], v[50:51], v[170:171] op_sel_hi:[1,0]
	v_pk_mul_f32 v[48:49], v[48:49], v[170:171] op_sel_hi:[1,0]
	v_pk_mul_f32 v[46:47], v[46:47], v[170:171] op_sel_hi:[1,0]
	v_pk_mul_f32 v[44:45], v[44:45], v[170:171] op_sel_hi:[1,0]
	v_pk_mul_f32 v[42:43], v[42:43], v[170:171] op_sel_hi:[1,0]
	v_pk_mul_f32 v[40:41], v[40:41], v[170:171] op_sel_hi:[1,0]
	v_pk_mul_f32 v[38:39], v[38:39], v[170:171] op_sel_hi:[1,0]
	v_pk_mul_f32 v[36:37], v[36:37], v[170:171] op_sel_hi:[1,0]
	v_pk_mul_f32 v[34:35], v[34:35], v[170:171] op_sel_hi:[1,0]
	v_pk_mul_f32 v[32:33], v[32:33], v[170:171] op_sel_hi:[1,0]
	v_pk_mul_f32 v[30:31], v[30:31], v[170:171] op_sel_hi:[1,0]
	v_pk_mul_f32 v[28:29], v[28:29], v[170:171] op_sel_hi:[1,0]
	v_pk_mul_f32 v[26:27], v[26:27], v[170:171] op_sel_hi:[1,0]
	v_pk_mul_f32 v[24:25], v[24:25], v[170:171] op_sel_hi:[1,0]
	v_pk_mul_f32 v[22:23], v[22:23], v[170:171] op_sel_hi:[1,0]
	v_pk_mul_f32 v[20:21], v[20:21], v[170:171] op_sel_hi:[1,0]
	v_pk_mul_f32 v[98:99], v[98:99], v[170:171] op_sel_hi:[1,0]
	v_pk_mul_f32 v[96:97], v[96:97], v[170:171] op_sel_hi:[1,0]
	v_pk_mul_f32 v[94:95], v[94:95], v[170:171] op_sel_hi:[1,0]
	v_pk_mul_f32 v[92:93], v[92:93], v[170:171] op_sel_hi:[1,0]
	v_pk_mul_f32 v[90:91], v[90:91], v[170:171] op_sel_hi:[1,0]
	v_pk_mul_f32 v[88:89], v[88:89], v[170:171] op_sel_hi:[1,0]
	v_pk_mul_f32 v[86:87], v[86:87], v[170:171] op_sel_hi:[1,0]
	v_pk_mul_f32 v[84:85], v[84:85], v[170:171] op_sel_hi:[1,0]
.LBB0_567:
	s_mov_b32 s14, s12
	s_mov_b32 s15, s12
	v_exp_f32_e32 v168, v116
	v_exp_f32_e32 v169, v117
	v_exp_f32_e32 v170, v118
	v_exp_f32_e32 v171, v119
	s_mov_b32 s13, s12
	v_mov_b64_e32 v[118:119], s[14:15]
	v_exp_f32_e32 v172, v120
	v_exp_f32_e32 v173, v121
	v_exp_f32_e32 v174, v122
	v_exp_f32_e32 v123, v123
	v_mov_b64_e32 v[116:117], s[12:13]
	v_cvt_pk_bf16_f32 v120, v168, v169
	v_cvt_pk_bf16_f32 v121, v170, v171
	v_cvt_pk_bf16_f32 v122, v172, v173
	v_cvt_pk_bf16_f32 v123, v174, v123
	v_exp_f32_e32 v124, v124
	v_exp_f32_e32 v125, v125
	v_mfma_f32_32x32x16_bf16 v[84:99], v[116:119], v[120:123], v[84:99]
	v_exp_f32_e32 v126, v126
	v_exp_f32_e32 v127, v127
	v_exp_f32_e32 v128, v128
	v_exp_f32_e32 v129, v129
	v_exp_f32_e32 v130, v130
	v_exp_f32_e32 v131, v131
	v_cvt_pk_bf16_f32 v124, v124, v125
	v_mfma_f32_32x32x16_bf16 v[36:51], v[152:155], v[120:123], v[36:51]
	v_cvt_pk_bf16_f32 v125, v126, v127
	v_cvt_pk_bf16_f32 v126, v128, v129
	v_cvt_pk_bf16_f32 v127, v130, v131
	v_mfma_f32_32x32x16_bf16 v[20:35], v[160:163], v[120:123], v[20:35]
	s_nop 0
	v_mfma_f32_32x32x16_bf16 v[84:99], v[116:119], v[124:127], v[84:99]
	v_mfma_f32_32x32x16_bf16 v[36:51], v[156:159], v[124:127], v[36:51]
	v_mfma_f32_32x32x16_bf16 v[20:35], v[164:167], v[124:127], v[20:35]

.LBB0_569:
	v_readfirstlane_b32 s13, v252
	s_and_b64 vcc, exec, s[28:29]
	s_cbranch_vccz .LBB0_571
	s_load_dwordx2 s[8:9], s[10:11], 0x58
	s_lshl_b32 s14, s25, 2
	v_mov_b32_e32 v2, s14
	s_mov_b64 s[14:15], 0xb800000
	s_mov_b64 s[30:31], 0
	s_waitcnt lgkmcnt(0)
	global_load_dword v2, v2, s[8:9]
	s_waitcnt vmcnt(0)
	v_mul_f32_e32 v85, 0x3fb8aa3b, v2
	s_branch .LBB0_572
